# layer-0 LN2 no longer writes its f32 output: per-row stats go to the unused upper half of the output buffer and the layer-1 WO epilogue applies that LayerNorm on the fly (hand-written LN2 phase)
# baseline (speedup 1.0000x reference)
; #define PG8_STAGE(bufoff, gbase, voff) do { _Pragma("unroll") for (int _i = 0; _i < 2; ++_i) \
;     __builtin_amdgcn_global_load_lds((const unsigned*)((const char*)(gbase) + (voff)[_i]), (LAS unsigned*)(lds + (bufoff) + ldsw + _i * 8192), 16, 0, 0); } while (0)
; #define PG8_LDA(dst, b, h) do { _Pragma("unroll") for (int m = 0; m < 4; ++m) _Pragma("unroll") for (int k = 0; k < 2; ++k) dst[m][k] = *(const LAS bf16x8*)(lds + PG8_SA(b, h) + aoff + m * 2048 + k * 1024); } while (0)
; #define PG8_LDB(dst, b, h) do { _Pragma("unroll") for (int n = 0; n < 2; ++n) _Pragma("unroll") for (int k = 0; k < 2; ++k) dst[n][k] = *(const LAS bf16x8*)(lds + PG8_SB(b, h) + boff + n * 2048 + k * 1024); } while (0)
; #define PG8_MMA(ai, bj, At, Bt) do { __builtin_amdgcn_s_setprio(1); _Pragma("unroll") for (int m = 0; m < 4; ++m) _Pragma("unroll") for (int n = 0; n < 2; ++n) _Pragma("unroll") for (int k = 0; k < 2; ++k) \
;     acc[ai][bj][m][n] = __builtin_amdgcn_mfma_f32_16x16x32_bf16(Bt[n][k], At[m][k], acc[ai][bj][m][n], 0, 0, 0); __builtin_amdgcn_s_setprio(0); } while (0)
; template <class Epi>
; __device__ __forceinline__ void gemm_phase(LAS unsigned char* lds, const Gemm g, const StaticOrder& S, const Epi& E, int wv0) {
;     ...
;       PG8_LDB(B0, 0, 0); PG8_SCHED; PG8_LDA(At, 0, 0); PG8_STAGE(PG8_SA(1, 1), a1 + hstepA, voffA);
;       PG8_WAIT_L(8); PG8_BAR; PG8_WAIT_L(0); PG8_MMA(0, 0, At, B0); PG8_BAR; PG8_SCHED;
;       PG8_LDB(B1, 0, 1); PG8_STAGE(PG8_SB(0, 0), b2, voffB);
;       PG8_BAR; PG8_WAIT_L(0); PG8_MMA(0, 1, At, B1); PG8_BAR;
;       PG8_LDA(At, 0, 1); PG8_STAGE(PG8_SA(0, 0), a2, voffA);
;       PG8_BAR; PG8_WAIT_L(0); PG8_MMA(1, 0, At, B0); PG8_BAR; PG8_SCHED;
;       PG8_STAGE(PG8_SB(0, 1), b2 + hstepB, voffB);
;       PG8_WAIT_V(6); PG8_BAR; PG8_MMA(1, 1, At, B1); PG8_BAR;
;       PG8_LDB(B0, 1, 0); PG8_SCHED; PG8_LDA(At, 1, 0); PG8_STAGE(PG8_SA(0, 1), a2 + hstepA, voffA);
;       PG8_WAIT_L(8); PG8_BAR; PG8_WAIT_L(0); PG8_MMA(0, 0, At, B0); PG8_BAR; PG8_SCHED;
;       PG8_LDB(B1, 1, 1); PG8_STAGE(PG8_SB(1, 0), b3, voffB);
;       PG8_BAR; PG8_WAIT_L(0); PG8_MMA(0, 1, At, B1); PG8_BAR;
;       PG8_LDA(At, 1, 1); PG8_STAGE(PG8_SA(1, 0), a3, voffA);
;       PG8_BAR; PG8_WAIT_L(0); PG8_MMA(1, 0, At, B0); PG8_BAR; PG8_SCHED;
;       PG8_STAGE(PG8_SB(1, 1), b3 + hstepB, voffB);
;       PG8_WAIT_V(6); PG8_BAR; PG8_MMA(1, 1, At, B1); PG8_BAR;
.LBB0_1100:
	s_add_u32 s0, s20, 0xfff80080
	s_addc_u32 s22, s21, -1
	s_add_i32 s50, 0, 0x10000
	v_add_u32_e32 v142, s50, v185
	ds_read_b128 v[130:133], v142
	ds_read_b128 v[134:137], v142 offset:1024
	ds_read_b128 v[138:141], v142 offset:2048
	ds_read_b128 v[142:145], v142 offset:3072
	s_cmp_eq_u32 s49, 28
	s_cselect_b32 s25, s13, s22
	s_cselect_b32 s24, s45, s0
	s_cselect_b32 s23, s11, s48
	s_cselect_b32 s22, s46, s47
	v_lshl_add_u64 v[192:193], s[20:21], 0, v[168:169]
	s_add_i32 m0, s19, 0xc000
	ds_read_b128 v[146:149], v187
	ds_read_b128 v[150:153], v187 offset:1024
	ds_read_b128 v[154:157], v187 offset:2048
	ds_read_b128 v[158:161], v187 offset:3072
	ds_read_b128 v[172:175], v187 offset:4096
	ds_read_b128 v[176:179], v187 offset:5120
	ds_read_b128 v[180:183], v187 offset:6144
	ds_read_b128 v[188:191], v187 offset:7168
	global_load_lds_dwordx4 v[192:193], off
	v_lshl_add_u64 v[192:193], s[20:21], 0, v[170:171]
	s_add_i32 m0, s19, 0xe000
	s_nop 0
	global_load_lds_dwordx4 v[192:193], off
	s_waitcnt lgkmcnt(8)
	s_barrier
	s_waitcnt lgkmcnt(0)
	s_setprio 1
	s_waitcnt lgkmcnt(0)
	v_mfma_f32_16x16x32_bf16 v[126:129], v[130:133], v[146:149], v[126:129]
	v_mfma_f32_16x16x32_bf16 v[122:125], v[138:141], v[146:149], v[122:125]
	v_mfma_f32_16x16x32_bf16 v[118:121], v[130:133], v[154:157], v[118:121]
	v_mfma_f32_16x16x32_bf16 v[114:117], v[138:141], v[154:157], v[114:117]
	v_mfma_f32_16x16x32_bf16 v[92:95], v[130:133], v[172:175], v[92:95]
	v_mfma_f32_16x16x32_bf16 v[88:91], v[138:141], v[172:175], v[88:91]
	v_mfma_f32_16x16x32_bf16 v[84:87], v[130:133], v[180:183], v[84:87]
	v_mfma_f32_16x16x32_bf16 v[76:79], v[138:141], v[180:183], v[76:79]
	v_mfma_f32_16x16x32_bf16 v[126:129], v[134:137], v[150:153], v[126:129]
	v_mfma_f32_16x16x32_bf16 v[122:125], v[142:145], v[150:153], v[122:125]
	v_mfma_f32_16x16x32_bf16 v[118:121], v[134:137], v[158:161], v[118:121]
	v_mfma_f32_16x16x32_bf16 v[114:117], v[142:145], v[158:161], v[114:117]
	v_mfma_f32_16x16x32_bf16 v[92:95], v[134:137], v[176:179], v[92:95]
	v_mfma_f32_16x16x32_bf16 v[88:91], v[142:145], v[176:179], v[88:91]
	v_mfma_f32_16x16x32_bf16 v[84:87], v[134:137], v[188:191], v[84:87]
	v_mfma_f32_16x16x32_bf16 v[76:79], v[142:145], v[188:191], v[76:79]
	s_setprio 0
	s_barrier
	s_add_i32 s0, 0, 0x14000
	s_add_i32 s50, s50, s31
	v_add_u32_e32 v204, s0, v185
	v_lshl_add_u64 v[208:209], s[22:23], 0, v[96:97]
	s_mov_b32 m0, s50
	ds_read_b128 v[192:195], v204
	ds_read_b128 v[196:199], v204 offset:1024
	ds_read_b128 v[200:203], v204 offset:2048
	ds_read_b128 v[204:207], v204 offset:3072
	global_load_lds_dwordx4 v[208:209], off
	v_lshl_add_u64 v[210:211], s[22:23], 0, v[166:167]
	s_add_i32 m0, s50, 0x2000
	s_nop 0
	global_load_lds_dwordx4 v[210:211], off
	s_barrier
	s_waitcnt lgkmcnt(0)
	s_setprio 1
	s_waitcnt lgkmcnt(0)
	v_mfma_f32_16x16x32_bf16 v[110:113], v[192:195], v[146:149], v[110:113]
	v_mfma_f32_16x16x32_bf16 v[106:109], v[200:203], v[146:149], v[106:109]
	v_mfma_f32_16x16x32_bf16 v[102:105], v[192:195], v[154:157], v[102:105]
	v_mfma_f32_16x16x32_bf16 v[98:101], v[200:203], v[154:157], v[98:101]
	v_mfma_f32_16x16x32_bf16 v[80:83], v[192:195], v[172:175], v[80:83]
	v_mfma_f32_16x16x32_bf16 v[72:75], v[200:203], v[172:175], v[72:75]
	v_mfma_f32_16x16x32_bf16 v[68:71], v[192:195], v[180:183], v[68:71]
	v_mfma_f32_16x16x32_bf16 v[64:67], v[200:203], v[180:183], v[64:67]
	v_mfma_f32_16x16x32_bf16 v[110:113], v[196:199], v[150:153], v[110:113]
	v_mfma_f32_16x16x32_bf16 v[106:109], v[204:207], v[150:153], v[106:109]
	v_mfma_f32_16x16x32_bf16 v[102:105], v[196:199], v[158:161], v[102:105]
	v_mfma_f32_16x16x32_bf16 v[98:101], v[204:207], v[158:161], v[98:101]
	v_mfma_f32_16x16x32_bf16 v[80:83], v[196:199], v[176:179], v[80:83]
	v_mfma_f32_16x16x32_bf16 v[72:75], v[204:207], v[176:179], v[72:75]
	v_mfma_f32_16x16x32_bf16 v[68:71], v[196:199], v[188:191], v[68:71]
	v_mfma_f32_16x16x32_bf16 v[64:67], v[204:207], v[188:191], v[64:67]
	s_setprio 0
	s_mov_b32 m0, s19
	v_lshl_add_u64 v[212:213], s[24:25], 0, v[162:163]
	s_barrier
	ds_read_b128 v[146:149], v187 offset:16384
	ds_read_b128 v[150:153], v187 offset:17408
	ds_read_b128 v[154:157], v187 offset:18432
	ds_read_b128 v[158:161], v187 offset:19456
	ds_read_b128 v[172:175], v187 offset:20480
	ds_read_b128 v[176:179], v187 offset:21504
	ds_read_b128 v[180:183], v187 offset:22528
	ds_read_b128 v[188:191], v187 offset:23552
	global_load_lds_dwordx4 v[212:213], off
	v_lshl_add_u64 v[214:215], s[24:25], 0, v[164:165]
	s_mov_b32 m0, s38
	s_nop 0
	global_load_lds_dwordx4 v[214:215], off
	s_barrier
	s_waitcnt lgkmcnt(0)
	s_setprio 1
	s_waitcnt lgkmcnt(0)
	v_mfma_f32_16x16x32_bf16 v[60:63], v[130:133], v[146:149], v[60:63]
	v_mfma_f32_16x16x32_bf16 v[56:59], v[138:141], v[146:149], v[56:59]
	v_mfma_f32_16x16x32_bf16 v[44:47], v[130:133], v[154:157], v[44:47]
	v_mfma_f32_16x16x32_bf16 v[40:43], v[138:141], v[154:157], v[40:43]
	v_mfma_f32_16x16x32_bf16 v[28:31], v[130:133], v[172:175], v[28:31]
	v_mfma_f32_16x16x32_bf16 v[24:27], v[138:141], v[172:175], v[24:27]
	v_mfma_f32_16x16x32_bf16 v[20:23], v[130:133], v[180:183], v[20:23]
	v_mfma_f32_16x16x32_bf16 v[8:11], v[138:141], v[180:183], v[8:11]
	v_mfma_f32_16x16x32_bf16 v[60:63], v[134:137], v[150:153], v[60:63]
	v_mfma_f32_16x16x32_bf16 v[56:59], v[142:145], v[150:153], v[56:59]
	v_mfma_f32_16x16x32_bf16 v[44:47], v[134:137], v[158:161], v[44:47]
	v_mfma_f32_16x16x32_bf16 v[40:43], v[142:145], v[158:161], v[40:43]
	v_mfma_f32_16x16x32_bf16 v[28:31], v[134:137], v[176:179], v[28:31]
	v_mfma_f32_16x16x32_bf16 v[24:27], v[142:145], v[176:179], v[24:27]
	v_mfma_f32_16x16x32_bf16 v[20:23], v[134:137], v[188:191], v[20:23]
	v_mfma_f32_16x16x32_bf16 v[8:11], v[142:145], v[188:191], v[8:11]
	s_setprio 0
	s_barrier
; #define PG8_STAGE(bufoff, gbase, voff) do { _Pragma("unroll") for (int _i = 0; _i < 2; ++_i) \
;     __builtin_amdgcn_global_load_lds((const unsigned*)((const char*)(gbase) + (voff)[_i]), (LAS unsigned*)(lds + (bufoff) + ldsw + _i * 8192), 16, 0, 0); } while (0)
; #define PG8_LDA(dst, b, h) do { _Pragma("unroll") for (int m = 0; m < 4; ++m) _Pragma("unroll") for (int k = 0; k < 2; ++k) dst[m][k] = *(const LAS bf16x8*)(lds + PG8_SA(b, h) + aoff + m * 2048 + k * 1024); } while (0)
; #define PG8_LDB(dst, b, h) do { _Pragma("unroll") for (int n = 0; n < 2; ++n) _Pragma("unroll") for (int k = 0; k < 2; ++k) dst[n][k] = *(const LAS bf16x8*)(lds + PG8_SB(b, h) + boff + n * 2048 + k * 1024); } while (0)
; #define PG8_MMA(ai, bj, At, Bt) do { __builtin_amdgcn_s_setprio(1); _Pragma("unroll") for (int m = 0; m < 4; ++m) _Pragma("unroll") for (int n = 0; n < 2; ++n) _Pragma("unroll") for (int k = 0; k < 2; ++k) \
;     acc[ai][bj][m][n] = __builtin_amdgcn_mfma_f32_16x16x32_bf16(Bt[n][k], At[m][k], acc[ai][bj][m][n], 0, 0, 0); __builtin_amdgcn_s_setprio(0); } while (0)
; template <class Epi>
; __device__ __forceinline__ void gemm_phase(LAS unsigned char* lds, const Gemm g, const StaticOrder& S, const Epi& E, int wv0) {
;     ...
;       PG8_LDB(B0, 0, 0); PG8_SCHED; PG8_LDA(At, 0, 0); PG8_STAGE(PG8_SA(1, 1), a1 + hstepA, voffA);
;       PG8_WAIT_L(8); PG8_BAR; PG8_WAIT_L(0); PG8_MMA(0, 0, At, B0); PG8_BAR; PG8_SCHED;
;       PG8_LDB(B1, 0, 1); PG8_STAGE(PG8_SB(0, 0), b2, voffB);
;       PG8_BAR; PG8_WAIT_L(0); PG8_MMA(0, 1, At, B1); PG8_BAR;
;       PG8_LDA(At, 0, 1); PG8_STAGE(PG8_SA(0, 0), a2, voffA);
;       PG8_BAR; PG8_WAIT_L(0); PG8_MMA(1, 0, At, B0); PG8_BAR; PG8_SCHED;
;       PG8_STAGE(PG8_SB(0, 1), b2 + hstepB, voffB);
;       PG8_WAIT_V(6); PG8_BAR; PG8_MMA(1, 1, At, B1); PG8_BAR;
;       PG8_LDB(B0, 1, 0); PG8_SCHED; PG8_LDA(At, 1, 0); PG8_STAGE(PG8_SA(0, 1), a2 + hstepA, voffA);
;       PG8_WAIT_L(8); PG8_BAR; PG8_WAIT_L(0); PG8_MMA(0, 0, At, B0); PG8_BAR; PG8_SCHED;
;       PG8_LDB(B1, 1, 1); PG8_STAGE(PG8_SB(1, 0), b3, voffB);
;       PG8_BAR; PG8_WAIT_L(0); PG8_MMA(0, 1, At, B1); PG8_BAR;
;       PG8_LDA(At, 1, 1); PG8_STAGE(PG8_SA(1, 0), a3, voffA);
;       PG8_BAR; PG8_WAIT_L(0); PG8_MMA(1, 0, At, B0); PG8_BAR; PG8_SCHED;
;       PG8_STAGE(PG8_SB(1, 1), b3 + hstepB, voffB);
;       PG8_WAIT_V(6); PG8_BAR; PG8_MMA(1, 1, At, B1); PG8_BAR;
	s_add_u32 s50, s22, 0x80000
	s_addc_u32 s51, s23, 0
	s_add_i32 s0, s0, s31
	v_lshl_add_u64 v[130:131], s[50:51], 0, v[96:97]
	s_mov_b32 m0, s0
	s_nop 0
	global_load_lds_dwordx4 v[130:131], off
	v_lshl_add_u64 v[130:131], s[50:51], 0, v[166:167]
	s_add_i32 m0, s0, 0x2000
	s_nop 0
	global_load_lds_dwordx4 v[130:131], off
	s_waitcnt vmcnt(6)
	s_barrier
	s_setprio 1
	v_mfma_f32_16x16x32_bf16 v[52:55], v[192:195], v[146:149], v[52:55]
	v_mfma_f32_16x16x32_bf16 v[48:51], v[200:203], v[146:149], v[48:51]
	v_mfma_f32_16x16x32_bf16 v[36:39], v[192:195], v[154:157], v[36:39]
	v_mfma_f32_16x16x32_bf16 v[32:35], v[200:203], v[154:157], v[32:35]
	v_mfma_f32_16x16x32_bf16 v[16:19], v[192:195], v[172:175], v[16:19]
	v_mfma_f32_16x16x32_bf16 v[12:15], v[200:203], v[172:175], v[12:15]
	v_mfma_f32_16x16x32_bf16 v[4:7], v[192:195], v[180:183], v[4:7]
	v_mfma_f32_16x16x32_bf16 v[0:3], v[200:203], v[180:183], v[0:3]
	v_mfma_f32_16x16x32_bf16 v[52:55], v[196:199], v[150:153], v[52:55]
	v_mfma_f32_16x16x32_bf16 v[48:51], v[204:207], v[150:153], v[48:51]
	v_mfma_f32_16x16x32_bf16 v[36:39], v[196:199], v[158:161], v[36:39]
	v_mfma_f32_16x16x32_bf16 v[32:35], v[204:207], v[158:161], v[32:35]
	v_mfma_f32_16x16x32_bf16 v[16:19], v[196:199], v[176:179], v[16:19]
	v_mfma_f32_16x16x32_bf16 v[12:15], v[204:207], v[176:179], v[12:15]
	v_mfma_f32_16x16x32_bf16 v[4:7], v[196:199], v[188:191], v[4:7]
	v_mfma_f32_16x16x32_bf16 v[0:3], v[204:207], v[188:191], v[0:3]
	s_setprio 0
	s_add_i32 s0, 0, 0x18000
	v_add_u32_e32 v142, s0, v185
	s_barrier
	ds_read_b128 v[130:133], v142
	ds_read_b128 v[134:137], v142 offset:1024
	ds_read_b128 v[138:141], v142 offset:2048
	ds_read_b128 v[142:145], v142 offset:3072
	s_add_u32 s24, s24, 0x80000
	s_addc_u32 s25, s25, 0
	s_mov_b32 m0, s39
	v_lshl_add_u64 v[192:193], s[24:25], 0, v[162:163]
	ds_read_b128 v[146:149], v187 offset:32768
	ds_read_b128 v[150:153], v187 offset:33792
	ds_read_b128 v[154:157], v187 offset:34816
	ds_read_b128 v[158:161], v187 offset:35840
	ds_read_b128 v[172:175], v187 offset:36864
	ds_read_b128 v[176:179], v187 offset:37888
	ds_read_b128 v[180:183], v187 offset:38912
	ds_read_b128 v[188:191], v187 offset:39936
	global_load_lds_dwordx4 v[192:193], off
	v_lshl_add_u64 v[192:193], s[24:25], 0, v[164:165]
	s_mov_b32 m0, s40
	s_nop 0
	global_load_lds_dwordx4 v[192:193], off
	s_waitcnt lgkmcnt(8)
	s_barrier
	s_waitcnt lgkmcnt(0)
	s_setprio 1
	s_waitcnt lgkmcnt(0)
	v_mfma_f32_16x16x32_bf16 v[126:129], v[130:133], v[146:149], v[126:129]
	v_mfma_f32_16x16x32_bf16 v[122:125], v[138:141], v[146:149], v[122:125]
	v_mfma_f32_16x16x32_bf16 v[118:121], v[130:133], v[154:157], v[118:121]
	v_mfma_f32_16x16x32_bf16 v[114:117], v[138:141], v[154:157], v[114:117]
	v_mfma_f32_16x16x32_bf16 v[92:95], v[130:133], v[172:175], v[92:95]
	v_mfma_f32_16x16x32_bf16 v[88:91], v[138:141], v[172:175], v[88:91]
	v_mfma_f32_16x16x32_bf16 v[84:87], v[130:133], v[180:183], v[84:87]
	v_mfma_f32_16x16x32_bf16 v[76:79], v[138:141], v[180:183], v[76:79]
	v_mfma_f32_16x16x32_bf16 v[126:129], v[134:137], v[150:153], v[126:129]
	v_mfma_f32_16x16x32_bf16 v[122:125], v[142:145], v[150:153], v[122:125]
	v_mfma_f32_16x16x32_bf16 v[118:121], v[134:137], v[158:161], v[118:121]
	v_mfma_f32_16x16x32_bf16 v[114:117], v[142:145], v[158:161], v[114:117]
	v_mfma_f32_16x16x32_bf16 v[92:95], v[134:137], v[176:179], v[92:95]
	v_mfma_f32_16x16x32_bf16 v[88:91], v[142:145], v[176:179], v[88:91]
	v_mfma_f32_16x16x32_bf16 v[84:87], v[134:137], v[188:191], v[84:87]
	v_mfma_f32_16x16x32_bf16 v[76:79], v[142:145], v[188:191], v[76:79]
	s_setprio 0
	s_barrier
	s_add_i32 s24, 0, 0x1c000
	s_add_i32 s0, s0, s31
	v_add_u32_e32 v204, s24, v185
	v_lshl_add_u64 v[208:209], v[208:209], 0, s[72:73]
	s_mov_b32 m0, s0
	ds_read_b128 v[192:195], v204
	ds_read_b128 v[196:199], v204 offset:1024
	ds_read_b128 v[200:203], v204 offset:2048
	ds_read_b128 v[204:207], v204 offset:3072
	global_load_lds_dwordx4 v[208:209], off
	v_lshl_add_u64 v[208:209], v[210:211], 0, s[72:73]
	s_add_i32 m0, s0, 0x2000
	s_nop 0
	global_load_lds_dwordx4 v[208:209], off
	s_barrier
	s_waitcnt lgkmcnt(0)
	s_setprio 1
	s_waitcnt lgkmcnt(0)
	v_mfma_f32_16x16x32_bf16 v[110:113], v[192:195], v[146:149], v[110:113]
	v_mfma_f32_16x16x32_bf16 v[106:109], v[200:203], v[146:149], v[106:109]
	v_mfma_f32_16x16x32_bf16 v[102:105], v[192:195], v[154:157], v[102:105]
	v_mfma_f32_16x16x32_bf16 v[98:101], v[200:203], v[154:157], v[98:101]
	v_mfma_f32_16x16x32_bf16 v[80:83], v[192:195], v[172:175], v[80:83]
	v_mfma_f32_16x16x32_bf16 v[72:75], v[200:203], v[172:175], v[72:75]
	v_mfma_f32_16x16x32_bf16 v[68:71], v[192:195], v[180:183], v[68:71]
	v_mfma_f32_16x16x32_bf16 v[64:67], v[200:203], v[180:183], v[64:67]
	v_mfma_f32_16x16x32_bf16 v[110:113], v[196:199], v[150:153], v[110:113]
	v_mfma_f32_16x16x32_bf16 v[106:109], v[204:207], v[150:153], v[106:109]
	v_mfma_f32_16x16x32_bf16 v[102:105], v[196:199], v[158:161], v[102:105]
	v_mfma_f32_16x16x32_bf16 v[98:101], v[204:207], v[158:161], v[98:101]
	v_mfma_f32_16x16x32_bf16 v[80:83], v[196:199], v[176:179], v[80:83]
	v_mfma_f32_16x16x32_bf16 v[72:75], v[204:207], v[176:179], v[72:75]
	v_mfma_f32_16x16x32_bf16 v[68:71], v[196:199], v[188:191], v[68:71]
	v_mfma_f32_16x16x32_bf16 v[64:67], v[204:207], v[188:191], v[64:67]
	s_setprio 0
	s_mov_b32 m0, s41
	v_lshl_add_u64 v[208:209], v[212:213], 0, s[72:73]
	s_barrier
	ds_read_b128 v[146:149], v187 offset:49152
	ds_read_b128 v[150:153], v187 offset:50176
	ds_read_b128 v[154:157], v187 offset:51200
	ds_read_b128 v[158:161], v187 offset:52224
	ds_read_b128 v[172:175], v187 offset:53248
	ds_read_b128 v[176:179], v187 offset:54272
	ds_read_b128 v[180:183], v187 offset:55296
	ds_read_b128 v[188:191], v187 offset:56320
	global_load_lds_dwordx4 v[208:209], off
	v_lshl_add_u64 v[208:209], v[214:215], 0, s[72:73]
	s_mov_b32 m0, s42
	s_nop 0
	global_load_lds_dwordx4 v[208:209], off
	s_barrier
; #define PG8_STAGE(bufoff, gbase, voff) do { _Pragma("unroll") for (int _i = 0; _i < 2; ++_i) \
;     __builtin_amdgcn_global_load_lds((const unsigned*)((const char*)(gbase) + (voff)[_i]), (LAS unsigned*)(lds + (bufoff) + ldsw + _i * 8192), 16, 0, 0); } while (0)
; #define PG8_LDA(dst, b, h) do { _Pragma("unroll") for (int m = 0; m < 4; ++m) _Pragma("unroll") for (int k = 0; k < 2; ++k) dst[m][k] = *(const LAS bf16x8*)(lds + PG8_SA(b, h) + aoff + m * 2048 + k * 1024); } while (0)
; #define PG8_LDB(dst, b, h) do { _Pragma("unroll") for (int n = 0; n < 2; ++n) _Pragma("unroll") for (int k = 0; k < 2; ++k) dst[n][k] = *(const LAS bf16x8*)(lds + PG8_SB(b, h) + boff + n * 2048 + k * 1024); } while (0)
; #define PG8_WAIT_V(n) asm volatile("s_waitcnt vmcnt(" #n ")" ::: "memory")
; #define PG8_WAIT_L(n) asm volatile("s_waitcnt lgkmcnt(" #n ")" ::: "memory")
; #define PG8_BAR __builtin_amdgcn_s_barrier()
; #define PG8_SCHED __builtin_amdgcn_sched_barrier(0)
; template <class Epi>
; __device__ __forceinline__ void gemm_phase(LAS unsigned char* lds, const Gemm g, const StaticOrder& S, const Epi& E, int wv0) {
;     ...
;       PG8_WAIT_V(6); PG8_BAR; PG8_MMA(1, 1, At, B1); PG8_BAR;
;       PG8_LDB(B0, 1, 0); PG8_SCHED; PG8_LDA(At, 1, 0); PG8_STAGE(PG8_SA(0, 1), a2 + hstepA, voffA);
;       PG8_WAIT_L(8); PG8_BAR; PG8_WAIT_L(0); PG8_MMA(0, 0, At, B0); PG8_BAR; PG8_SCHED;
;       PG8_LDB(B1, 1, 1); PG8_STAGE(PG8_SB(1, 0), b3, voffB);
;       PG8_BAR; PG8_WAIT_L(0); PG8_MMA(0, 1, At, B1); PG8_BAR;
;       PG8_LDA(At, 1, 1); PG8_STAGE(PG8_SA(1, 0), a3, voffA);
;       PG8_BAR; PG8_WAIT_L(0); PG8_MMA(1, 0, At, B0); PG8_BAR; PG8_SCHED;
;       PG8_STAGE(PG8_SB(1, 1), b3 + hstepB, voffB);
;       PG8_WAIT_V(6); PG8_BAR; PG8_MMA(1, 1, At, B1); PG8_BAR;
;     }
;   __device__ __forceinline__ void emit(const EpiPre& q0, int row, int col, f32x4 a, f32x4 b, const f32x4 (&hb)[2][2], const float (&hs)[2][4], int ai_, int m_, int bj_) const {
;     ...
;     } else if (MODE == E_RES) {
;       const f32x4 r0 = q.a0, r1 = q.a1;
;       float* o = (float*)e.out + (size_t)row * DM + col;
;       *(f32x4*)o = (f32x4){ALPHA * r0[0] + v[0], ALPHA * r0[1] + v[1], ALPHA * r0[2] + v[2], ALPHA * r0[3] + v[3]};
;       *(f32x4*)(o + 4) = (f32x4){ALPHA * r1[0] + v[4], ALPHA * r1[1] + v[5], ALPHA * r1[2] + v[6], ALPHA * r1[3] + v[7]};
	s_waitcnt lgkmcnt(0)
	s_setprio 1
	s_waitcnt lgkmcnt(0)
	v_mfma_f32_16x16x32_bf16 v[60:63], v[130:133], v[146:149], v[60:63]
	v_mfma_f32_16x16x32_bf16 v[56:59], v[138:141], v[146:149], v[56:59]
	v_mfma_f32_16x16x32_bf16 v[44:47], v[130:133], v[154:157], v[44:47]
	v_mfma_f32_16x16x32_bf16 v[40:43], v[138:141], v[154:157], v[40:43]
	v_mfma_f32_16x16x32_bf16 v[28:31], v[130:133], v[172:175], v[28:31]
	v_mfma_f32_16x16x32_bf16 v[24:27], v[138:141], v[172:175], v[24:27]
	v_mfma_f32_16x16x32_bf16 v[20:23], v[130:133], v[180:183], v[20:23]
	v_mfma_f32_16x16x32_bf16 v[8:11], v[138:141], v[180:183], v[8:11]
	v_mfma_f32_16x16x32_bf16 v[60:63], v[134:137], v[150:153], v[60:63]
	v_mfma_f32_16x16x32_bf16 v[56:59], v[142:145], v[150:153], v[56:59]
	v_mfma_f32_16x16x32_bf16 v[44:47], v[134:137], v[158:161], v[44:47]
	v_mfma_f32_16x16x32_bf16 v[40:43], v[142:145], v[158:161], v[40:43]
	v_mfma_f32_16x16x32_bf16 v[28:31], v[134:137], v[176:179], v[28:31]
	v_mfma_f32_16x16x32_bf16 v[24:27], v[142:145], v[176:179], v[24:27]
	v_mfma_f32_16x16x32_bf16 v[20:23], v[134:137], v[188:191], v[20:23]
	v_mfma_f32_16x16x32_bf16 v[8:11], v[142:145], v[188:191], v[8:11]
	s_setprio 0
	s_barrier
	s_add_u32 s22, s22, 0x80080
	s_addc_u32 s23, s23, 0
	s_add_i32 s0, s24, s31
	v_lshl_add_u64 v[130:131], s[22:23], 0, v[96:97]
	s_mov_b32 m0, s0
	s_nop 0
	global_load_lds_dwordx4 v[130:131], off
	v_lshl_add_u64 v[130:131], s[22:23], 0, v[166:167]
	s_add_i32 m0, s0, 0x2000
	s_nop 0
	global_load_lds_dwordx4 v[130:131], off
	s_waitcnt vmcnt(6)
	s_barrier
	s_setprio 1
	v_mfma_f32_16x16x32_bf16 v[52:55], v[192:195], v[146:149], v[52:55]
	v_mfma_f32_16x16x32_bf16 v[48:51], v[200:203], v[146:149], v[48:51]
	v_mfma_f32_16x16x32_bf16 v[36:39], v[192:195], v[154:157], v[36:39]
	v_mfma_f32_16x16x32_bf16 v[32:35], v[200:203], v[154:157], v[32:35]
	v_mfma_f32_16x16x32_bf16 v[16:19], v[192:195], v[172:175], v[16:19]
	v_mfma_f32_16x16x32_bf16 v[12:15], v[200:203], v[172:175], v[12:15]
	v_mfma_f32_16x16x32_bf16 v[4:7], v[192:195], v[180:183], v[4:7]
	v_mfma_f32_16x16x32_bf16 v[0:3], v[200:203], v[180:183], v[0:3]
	v_mfma_f32_16x16x32_bf16 v[52:55], v[196:199], v[150:153], v[52:55]
	v_mfma_f32_16x16x32_bf16 v[48:51], v[204:207], v[150:153], v[48:51]
	v_mfma_f32_16x16x32_bf16 v[36:39], v[196:199], v[158:161], v[36:39]
	v_mfma_f32_16x16x32_bf16 v[32:35], v[204:207], v[158:161], v[32:35]
	v_mfma_f32_16x16x32_bf16 v[16:19], v[196:199], v[176:179], v[16:19]
	v_mfma_f32_16x16x32_bf16 v[12:15], v[204:207], v[176:179], v[12:15]
	v_mfma_f32_16x16x32_bf16 v[4:7], v[196:199], v[188:191], v[4:7]
	v_mfma_f32_16x16x32_bf16 v[0:3], v[204:207], v[188:191], v[0:3]
	s_setprio 0
	s_add_i32 s49, s49, 2
	s_add_u32 s20, s20, 0x100
	s_addc_u32 s21, s21, 0
	s_add_u32 s47, s47, 0x100
	s_addc_u32 s48, s48, 0
	s_cmp_gt_u32 s49, 29
	s_barrier
	s_cbranch_scc0 .LBB0_1100
	s_cmp_eq_u32 s66, 0
	s_cbranch_scc1 .Lwo_plain
	s_load_dwordx4 s[48:51], s[54:55], 0xb8
	s_load_dwordx2 s[96:97], s[54:55], 0xc8
	v_lshl_add_u32 v243, s18, 8, v184
	v_lshl_or_b32 v247, s1, 8, v186
	v_lshlrev_b32_e32 v242, 13, v243
	v_lshlrev_b32_e32 v247, 2, v247
	v_lshlrev_b32_e32 v243, 3, v243
	v_add_u32_e32 v242, v242, v247
	s_waitcnt lgkmcnt(0)
	s_add_u32 s100, s96, 0x4000000
	s_addc_u32 s101, s97, 0
	s_add_u32 s20, s6, 0x0
	s_addc_u32 s21, s7, 0
	global_load_dwordx2 v[220:221], v243, s[100:101] offset:0
	global_load_dwordx4 v[130:133], v242, s[20:21]
	global_load_dwordx4 v[134:137], v242, s[20:21] offset:16
	global_load_dwordx4 v[138:141], v242, s[20:21] offset:512
	global_load_dwordx4 v[142:145], v242, s[20:21] offset:528
	s_add_u32 s22, s6, 0x20000
	s_addc_u32 s23, s7, 0
	global_load_dwordx2 v[238:239], v243, s[100:101] offset:128
	global_load_dwordx4 v[146:149], v242, s[22:23]
	global_load_dwordx4 v[150:153], v242, s[22:23] offset:16
	global_load_dwordx4 v[154:157], v242, s[22:23] offset:512
	global_load_dwordx4 v[158:161], v242, s[22:23] offset:528
	s_add_u32 s24, s6, 0x40000
	s_addc_u32 s25, s7, 0
	global_load_dwordx2 v[240:241], v243, s[100:101] offset:256
	global_load_dwordx4 v[172:175], v242, s[24:25]
	global_load_dwordx4 v[176:179], v242, s[24:25] offset:16
	global_load_dwordx4 v[180:183], v242, s[24:25] offset:512
	global_load_dwordx4 v[234:237], v242, s[24:25] offset:528
	global_load_dwordx4 v[188:191], v247, s[48:49]
	global_load_dwordx4 v[192:195], v247, s[48:49] offset:16
	global_load_dwordx4 v[196:199], v247, s[48:49] offset:512
	global_load_dwordx4 v[200:203], v247, s[48:49] offset:528
	global_load_dwordx4 v[204:207], v247, s[50:51]
	global_load_dwordx4 v[208:211], v247, s[50:51] offset:16
	global_load_dwordx4 v[212:215], v247, s[50:51] offset:512
	global_load_dwordx4 v[216:219], v247, s[50:51] offset:528
	s_waitcnt vmcnt(0)
;   __device__ __forceinline__ void emit(const EpiPre& q0, int row, int col, f32x4 a, f32x4 b, const f32x4 (&hb)[2][2], const float (&hs)[2][4], int ai_, int m_, int bj_) const {
;     ...
;     } else if (MODE == E_RES) {
;       const f32x4 r0 = q.a0, r1 = q.a1;
;       float* o = (float*)e.out + (size_t)row * DM + col;
;       *(f32x4*)o = (f32x4){ALPHA * r0[0] + v[0], ALPHA * r0[1] + v[1], ALPHA * r0[2] + v[2], ALPHA * r0[3] + v[3]};
;       *(f32x4*)(o + 4) = (f32x4){ALPHA * r1[0] + v[4], ALPHA * r1[1] + v[5], ALPHA * r1[2] + v[6], ALPHA * r1[3] + v[7]};
; __device__ __forceinline__ void ln_phase(const float* in, float* outf, bf16_t* outb, const float* g, const float* b, int wv0) {
;     ...
;     for (int i = 0; i < 8; ++i) {
;       const f32x4 y = v[i] * rstd * gg[i] + bb[i];
	v_pk_add_f32 v[130:131], v[130:131], v[220:221] op_sel_hi:[1,0]
	v_pk_add_f32 v[132:133], v[132:133], v[220:221] op_sel_hi:[1,0]
	v_pk_add_f32 v[134:135], v[134:135], v[220:221] op_sel_hi:[1,0]
	v_pk_add_f32 v[136:137], v[136:137], v[220:221] op_sel_hi:[1,0]
	v_pk_add_f32 v[138:139], v[138:139], v[220:221] op_sel_hi:[1,0]
	v_pk_add_f32 v[140:141], v[140:141], v[220:221] op_sel_hi:[1,0]
	v_pk_add_f32 v[142:143], v[142:143], v[220:221] op_sel_hi:[1,0]
	v_pk_add_f32 v[144:145], v[144:145], v[220:221] op_sel_hi:[1,0]
	v_pk_mul_f32 v[130:131], v[130:131], v[220:221] op_sel:[0,1] op_sel_hi:[1,1]
	v_pk_mul_f32 v[132:133], v[132:133], v[220:221] op_sel:[0,1] op_sel_hi:[1,1]
	v_pk_mul_f32 v[134:135], v[134:135], v[220:221] op_sel:[0,1] op_sel_hi:[1,1]
	v_pk_mul_f32 v[136:137], v[136:137], v[220:221] op_sel:[0,1] op_sel_hi:[1,1]
	v_pk_mul_f32 v[138:139], v[138:139], v[220:221] op_sel:[0,1] op_sel_hi:[1,1]
	v_pk_mul_f32 v[140:141], v[140:141], v[220:221] op_sel:[0,1] op_sel_hi:[1,1]
	v_pk_mul_f32 v[142:143], v[142:143], v[220:221] op_sel:[0,1] op_sel_hi:[1,1]
	v_pk_mul_f32 v[144:145], v[144:145], v[220:221] op_sel:[0,1] op_sel_hi:[1,1]
	v_pk_fma_f32 v[130:131], v[188:189], v[130:131], v[204:205]
	v_pk_fma_f32 v[132:133], v[190:191], v[132:133], v[206:207]
	v_pk_fma_f32 v[134:135], v[192:193], v[134:135], v[208:209]
	v_pk_fma_f32 v[136:137], v[194:195], v[136:137], v[210:211]
	v_pk_fma_f32 v[138:139], v[196:197], v[138:139], v[212:213]
	v_pk_fma_f32 v[140:141], v[198:199], v[140:141], v[214:215]
	v_pk_fma_f32 v[142:143], v[200:201], v[142:143], v[216:217]
	v_pk_fma_f32 v[144:145], v[202:203], v[144:145], v[218:219]
	v_pk_fma_f32 v[126:127], v[130:131], s[90:91], v[126:127] op_sel_hi:[1,0,1]
	v_pk_fma_f32 v[128:129], v[132:133], s[90:91], v[128:129] op_sel_hi:[1,0,1]
	v_pk_fma_f32 v[122:123], v[134:135], s[90:91], v[122:123] op_sel_hi:[1,0,1]
	v_pk_fma_f32 v[124:125], v[136:137], s[90:91], v[124:125] op_sel_hi:[1,0,1]
	v_pk_fma_f32 v[110:111], v[138:139], s[90:91], v[110:111] op_sel_hi:[1,0,1]
	v_pk_fma_f32 v[112:113], v[140:141], s[90:91], v[112:113] op_sel_hi:[1,0,1]
	v_pk_fma_f32 v[106:107], v[142:143], s[90:91], v[106:107] op_sel_hi:[1,0,1]
	v_pk_fma_f32 v[108:109], v[144:145], s[90:91], v[108:109] op_sel_hi:[1,0,1]
	s_add_u32 s46, s6, 0x60000
	s_addc_u32 s47, s7, 0
	global_load_dwordx2 v[220:221], v243, s[100:101] offset:384
	global_load_dwordx4 v[130:133], v242, s[46:47]
	global_load_dwordx4 v[134:137], v242, s[46:47] offset:16
	global_load_dwordx4 v[138:141], v242, s[46:47] offset:512
	global_load_dwordx4 v[142:145], v242, s[46:47] offset:528
	s_waitcnt vmcnt(18)
	v_pk_add_f32 v[146:147], v[146:147], v[238:239] op_sel_hi:[1,0]
	v_pk_add_f32 v[148:149], v[148:149], v[238:239] op_sel_hi:[1,0]
	v_pk_add_f32 v[150:151], v[150:151], v[238:239] op_sel_hi:[1,0]
	v_pk_add_f32 v[152:153], v[152:153], v[238:239] op_sel_hi:[1,0]
	v_pk_add_f32 v[154:155], v[154:155], v[238:239] op_sel_hi:[1,0]
	v_pk_add_f32 v[156:157], v[156:157], v[238:239] op_sel_hi:[1,0]
	v_pk_add_f32 v[158:159], v[158:159], v[238:239] op_sel_hi:[1,0]
	v_pk_add_f32 v[160:161], v[160:161], v[238:239] op_sel_hi:[1,0]
	v_pk_mul_f32 v[146:147], v[146:147], v[238:239] op_sel:[0,1] op_sel_hi:[1,1]
	v_pk_mul_f32 v[148:149], v[148:149], v[238:239] op_sel:[0,1] op_sel_hi:[1,1]
	v_pk_mul_f32 v[150:151], v[150:151], v[238:239] op_sel:[0,1] op_sel_hi:[1,1]
	v_pk_mul_f32 v[152:153], v[152:153], v[238:239] op_sel:[0,1] op_sel_hi:[1,1]
	v_pk_mul_f32 v[154:155], v[154:155], v[238:239] op_sel:[0,1] op_sel_hi:[1,1]
	v_pk_mul_f32 v[156:157], v[156:157], v[238:239] op_sel:[0,1] op_sel_hi:[1,1]
	v_pk_mul_f32 v[158:159], v[158:159], v[238:239] op_sel:[0,1] op_sel_hi:[1,1]
	v_pk_mul_f32 v[160:161], v[160:161], v[238:239] op_sel:[0,1] op_sel_hi:[1,1]
	v_pk_fma_f32 v[146:147], v[188:189], v[146:147], v[204:205]
	v_pk_fma_f32 v[148:149], v[190:191], v[148:149], v[206:207]
	v_pk_fma_f32 v[150:151], v[192:193], v[150:151], v[208:209]
	v_pk_fma_f32 v[152:153], v[194:195], v[152:153], v[210:211]
	v_pk_fma_f32 v[154:155], v[196:197], v[154:155], v[212:213]
	v_pk_fma_f32 v[156:157], v[198:199], v[156:157], v[214:215]
	v_pk_fma_f32 v[158:159], v[200:201], v[158:159], v[216:217]
	v_pk_fma_f32 v[160:161], v[202:203], v[160:161], v[218:219]
	v_pk_fma_f32 v[118:119], v[146:147], s[90:91], v[118:119] op_sel_hi:[1,0,1]
	v_pk_fma_f32 v[120:121], v[148:149], s[90:91], v[120:121] op_sel_hi:[1,0,1]
	v_pk_fma_f32 v[114:115], v[150:151], s[90:91], v[114:115] op_sel_hi:[1,0,1]
	v_pk_fma_f32 v[116:117], v[152:153], s[90:91], v[116:117] op_sel_hi:[1,0,1]
	v_pk_fma_f32 v[102:103], v[154:155], s[90:91], v[102:103] op_sel_hi:[1,0,1]
	v_pk_fma_f32 v[104:105], v[156:157], s[90:91], v[104:105] op_sel_hi:[1,0,1]
	v_pk_fma_f32 v[98:99], v[158:159], s[90:91], v[98:99] op_sel_hi:[1,0,1]
	v_pk_fma_f32 v[100:101], v[160:161], s[90:91], v[100:101] op_sel_hi:[1,0,1]
	s_add_u32 s48, s6, 0x100000
	s_addc_u32 s49, s7, 0
	global_load_dwordx2 v[238:239], v243, s[100:101] offset:1024
	global_load_dwordx4 v[146:149], v242, s[48:49]
	global_load_dwordx4 v[150:153], v242, s[48:49] offset:16
	global_load_dwordx4 v[154:157], v242, s[48:49] offset:512
	global_load_dwordx4 v[158:161], v242, s[48:49] offset:528
	s_waitcnt vmcnt(18)
;   __device__ __forceinline__ void emit(const EpiPre& q0, int row, int col, f32x4 a, f32x4 b, const f32x4 (&hb)[2][2], const float (&hs)[2][4], int ai_, int m_, int bj_) const {
;     ...
;     } else if (MODE == E_RES) {
;       const f32x4 r0 = q.a0, r1 = q.a1;
;       float* o = (float*)e.out + (size_t)row * DM + col;
;       *(f32x4*)o = (f32x4){ALPHA * r0[0] + v[0], ALPHA * r0[1] + v[1], ALPHA * r0[2] + v[2], ALPHA * r0[3] + v[3]};
;       *(f32x4*)(o + 4) = (f32x4){ALPHA * r1[0] + v[4], ALPHA * r1[1] + v[5], ALPHA * r1[2] + v[6], ALPHA * r1[3] + v[7]};
; __device__ __forceinline__ void ln_phase(const float* in, float* outf, bf16_t* outb, const float* g, const float* b, int wv0) {
;     ...
;     for (int i = 0; i < 8; ++i) {
;       const f32x4 y = v[i] * rstd * gg[i] + bb[i];
	v_pk_add_f32 v[172:173], v[172:173], v[240:241] op_sel_hi:[1,0]
	v_pk_add_f32 v[174:175], v[174:175], v[240:241] op_sel_hi:[1,0]
	v_pk_add_f32 v[176:177], v[176:177], v[240:241] op_sel_hi:[1,0]
	v_pk_add_f32 v[178:179], v[178:179], v[240:241] op_sel_hi:[1,0]
	v_pk_add_f32 v[180:181], v[180:181], v[240:241] op_sel_hi:[1,0]
	v_pk_add_f32 v[182:183], v[182:183], v[240:241] op_sel_hi:[1,0]
	v_pk_add_f32 v[234:235], v[234:235], v[240:241] op_sel_hi:[1,0]
	v_pk_add_f32 v[236:237], v[236:237], v[240:241] op_sel_hi:[1,0]
	v_pk_mul_f32 v[172:173], v[172:173], v[240:241] op_sel:[0,1] op_sel_hi:[1,1]
	v_pk_mul_f32 v[174:175], v[174:175], v[240:241] op_sel:[0,1] op_sel_hi:[1,1]
	v_pk_mul_f32 v[176:177], v[176:177], v[240:241] op_sel:[0,1] op_sel_hi:[1,1]
	v_pk_mul_f32 v[178:179], v[178:179], v[240:241] op_sel:[0,1] op_sel_hi:[1,1]
	v_pk_mul_f32 v[180:181], v[180:181], v[240:241] op_sel:[0,1] op_sel_hi:[1,1]
	v_pk_mul_f32 v[182:183], v[182:183], v[240:241] op_sel:[0,1] op_sel_hi:[1,1]
	v_pk_mul_f32 v[234:235], v[234:235], v[240:241] op_sel:[0,1] op_sel_hi:[1,1]
	v_pk_mul_f32 v[236:237], v[236:237], v[240:241] op_sel:[0,1] op_sel_hi:[1,1]
	v_pk_fma_f32 v[172:173], v[188:189], v[172:173], v[204:205]
	v_pk_fma_f32 v[174:175], v[190:191], v[174:175], v[206:207]
	v_pk_fma_f32 v[176:177], v[192:193], v[176:177], v[208:209]
	v_pk_fma_f32 v[178:179], v[194:195], v[178:179], v[210:211]
	v_pk_fma_f32 v[180:181], v[196:197], v[180:181], v[212:213]
	v_pk_fma_f32 v[182:183], v[198:199], v[182:183], v[214:215]
	v_pk_fma_f32 v[234:235], v[200:201], v[234:235], v[216:217]
	v_pk_fma_f32 v[236:237], v[202:203], v[236:237], v[218:219]
	v_pk_fma_f32 v[92:93], v[172:173], s[90:91], v[92:93] op_sel_hi:[1,0,1]
	v_pk_fma_f32 v[94:95], v[174:175], s[90:91], v[94:95] op_sel_hi:[1,0,1]
	v_pk_fma_f32 v[88:89], v[176:177], s[90:91], v[88:89] op_sel_hi:[1,0,1]
	v_pk_fma_f32 v[90:91], v[178:179], s[90:91], v[90:91] op_sel_hi:[1,0,1]
	v_pk_fma_f32 v[80:81], v[180:181], s[90:91], v[80:81] op_sel_hi:[1,0,1]
	v_pk_fma_f32 v[82:83], v[182:183], s[90:91], v[82:83] op_sel_hi:[1,0,1]
	v_pk_fma_f32 v[72:73], v[234:235], s[90:91], v[72:73] op_sel_hi:[1,0,1]
	v_pk_fma_f32 v[74:75], v[236:237], s[90:91], v[74:75] op_sel_hi:[1,0,1]
	s_add_u32 s50, s6, 0x120000
	s_addc_u32 s51, s7, 0
	global_load_dwordx2 v[240:241], v243, s[100:101] offset:1152
	global_load_dwordx4 v[172:175], v242, s[50:51]
	global_load_dwordx4 v[176:179], v242, s[50:51] offset:16
	global_load_dwordx4 v[180:183], v242, s[50:51] offset:512
	global_load_dwordx4 v[234:237], v242, s[50:51] offset:528
	global_store_dwordx4 v242, v[126:129], s[20:21]
	global_store_dwordx4 v242, v[122:125], s[20:21] offset:16
	global_store_dwordx4 v242, v[110:113], s[20:21] offset:512
	global_store_dwordx4 v242, v[106:109], s[20:21] offset:528
	global_store_dwordx4 v242, v[118:121], s[22:23]
	global_store_dwordx4 v242, v[114:117], s[22:23] offset:16
	global_store_dwordx4 v242, v[102:105], s[22:23] offset:512
	global_store_dwordx4 v242, v[98:101], s[22:23] offset:528
	global_store_dwordx4 v242, v[92:95], s[24:25]
	global_store_dwordx4 v242, v[88:91], s[24:25] offset:16
	global_store_dwordx4 v242, v[80:83], s[24:25] offset:512
	global_store_dwordx4 v242, v[72:75], s[24:25] offset:528
	s_add_u32 s20, s6, 0x140000
	s_addc_u32 s21, s7, 0
	global_load_dwordx2 v[92:93], v243, s[100:101] offset:1280
	global_load_dwordx4 v[126:129], v242, s[20:21]
	global_load_dwordx4 v[122:125], v242, s[20:21] offset:16
	global_load_dwordx4 v[110:113], v242, s[20:21] offset:512
	global_load_dwordx4 v[106:109], v242, s[20:21] offset:528
	s_add_u32 s22, s6, 0x160000
	s_addc_u32 s23, s7, 0
	global_load_dwordx2 v[88:89], v243, s[100:101] offset:1408
	global_load_dwordx4 v[118:121], v242, s[22:23]
	global_load_dwordx4 v[114:117], v242, s[22:23] offset:16
	global_load_dwordx4 v[102:105], v242, s[22:23] offset:512
	global_load_dwordx4 v[98:101], v242, s[22:23] offset:528
	s_waitcnt vmcnt(32)
	v_pk_add_f32 v[130:131], v[130:131], v[220:221] op_sel_hi:[1,0]
	v_pk_add_f32 v[132:133], v[132:133], v[220:221] op_sel_hi:[1,0]
	v_pk_add_f32 v[134:135], v[134:135], v[220:221] op_sel_hi:[1,0]
	v_pk_add_f32 v[136:137], v[136:137], v[220:221] op_sel_hi:[1,0]
	v_pk_add_f32 v[138:139], v[138:139], v[220:221] op_sel_hi:[1,0]
	v_pk_add_f32 v[140:141], v[140:141], v[220:221] op_sel_hi:[1,0]
	v_pk_add_f32 v[142:143], v[142:143], v[220:221] op_sel_hi:[1,0]
	v_pk_add_f32 v[144:145], v[144:145], v[220:221] op_sel_hi:[1,0]
	v_pk_mul_f32 v[130:131], v[130:131], v[220:221] op_sel:[0,1] op_sel_hi:[1,1]
	v_pk_mul_f32 v[132:133], v[132:133], v[220:221] op_sel:[0,1] op_sel_hi:[1,1]
	v_pk_mul_f32 v[134:135], v[134:135], v[220:221] op_sel:[0,1] op_sel_hi:[1,1]
	v_pk_mul_f32 v[136:137], v[136:137], v[220:221] op_sel:[0,1] op_sel_hi:[1,1]
	v_pk_mul_f32 v[138:139], v[138:139], v[220:221] op_sel:[0,1] op_sel_hi:[1,1]
	v_pk_mul_f32 v[140:141], v[140:141], v[220:221] op_sel:[0,1] op_sel_hi:[1,1]
	v_pk_mul_f32 v[142:143], v[142:143], v[220:221] op_sel:[0,1] op_sel_hi:[1,1]
	v_pk_mul_f32 v[144:145], v[144:145], v[220:221] op_sel:[0,1] op_sel_hi:[1,1]
	v_pk_fma_f32 v[130:131], v[188:189], v[130:131], v[204:205]
	v_pk_fma_f32 v[132:133], v[190:191], v[132:133], v[206:207]
	v_pk_fma_f32 v[134:135], v[192:193], v[134:135], v[208:209]
	v_pk_fma_f32 v[136:137], v[194:195], v[136:137], v[210:211]
	v_pk_fma_f32 v[138:139], v[196:197], v[138:139], v[212:213]
	v_pk_fma_f32 v[140:141], v[198:199], v[140:141], v[214:215]
	v_pk_fma_f32 v[142:143], v[200:201], v[142:143], v[216:217]
	v_pk_fma_f32 v[144:145], v[202:203], v[144:145], v[218:219]
	v_pk_fma_f32 v[84:85], v[130:131], s[90:91], v[84:85] op_sel_hi:[1,0,1]
	v_pk_fma_f32 v[86:87], v[132:133], s[90:91], v[86:87] op_sel_hi:[1,0,1]
	v_pk_fma_f32 v[76:77], v[134:135], s[90:91], v[76:77] op_sel_hi:[1,0,1]
	v_pk_fma_f32 v[78:79], v[136:137], s[90:91], v[78:79] op_sel_hi:[1,0,1]
	v_pk_fma_f32 v[68:69], v[138:139], s[90:91], v[68:69] op_sel_hi:[1,0,1]
	v_pk_fma_f32 v[70:71], v[140:141], s[90:91], v[70:71] op_sel_hi:[1,0,1]
	v_pk_fma_f32 v[64:65], v[142:143], s[90:91], v[64:65] op_sel_hi:[1,0,1]
	v_pk_fma_f32 v[66:67], v[144:145], s[90:91], v[66:67] op_sel_hi:[1,0,1]
	global_store_dwordx4 v242, v[84:87], s[46:47]
	global_store_dwordx4 v242, v[76:79], s[46:47] offset:16
	global_store_dwordx4 v242, v[68:71], s[46:47] offset:512
	global_store_dwordx4 v242, v[64:67], s[46:47] offset:528
	s_waitcnt vmcnt(31)
;   __device__ __forceinline__ void emit(const EpiPre& q0, int row, int col, f32x4 a, f32x4 b, const f32x4 (&hb)[2][2], const float (&hs)[2][4], int ai_, int m_, int bj_) const {
;     ...
;     } else if (MODE == E_RES) {
;       const f32x4 r0 = q.a0, r1 = q.a1;
;       float* o = (float*)e.out + (size_t)row * DM + col;
;       *(f32x4*)o = (f32x4){ALPHA * r0[0] + v[0], ALPHA * r0[1] + v[1], ALPHA * r0[2] + v[2], ALPHA * r0[3] + v[3]};
;       *(f32x4*)(o + 4) = (f32x4){ALPHA * r1[0] + v[4], ALPHA * r1[1] + v[5], ALPHA * r1[2] + v[6], ALPHA * r1[3] + v[7]};
; __device__ __forceinline__ void ln_phase(const float* in, float* outf, bf16_t* outb, const float* g, const float* b, int wv0) {
;     ...
;     for (int i = 0; i < 8; ++i) { v[i] -= mu; sq += v[i][0] * v[i][0] + v[i][1] * v[i][1] + v[i][2] * v[i][2] + v[i][3] * v[i][3]; }
;     sq = wave_sum(sq); const float rstd = __builtin_amdgcn_rsqf(sq * (1.0f / 2048.0f) + EPS);
; #pragma unroll
;     for (int i = 0; i < 8; ++i) {
;       const f32x4 y = v[i] * rstd * gg[i] + bb[i];
	v_pk_add_f32 v[146:147], v[146:147], v[238:239] op_sel_hi:[1,0]
	v_pk_add_f32 v[148:149], v[148:149], v[238:239] op_sel_hi:[1,0]
	v_pk_add_f32 v[150:151], v[150:151], v[238:239] op_sel_hi:[1,0]
	v_pk_add_f32 v[152:153], v[152:153], v[238:239] op_sel_hi:[1,0]
	v_pk_add_f32 v[154:155], v[154:155], v[238:239] op_sel_hi:[1,0]
	v_pk_add_f32 v[156:157], v[156:157], v[238:239] op_sel_hi:[1,0]
	v_pk_add_f32 v[158:159], v[158:159], v[238:239] op_sel_hi:[1,0]
	v_pk_add_f32 v[160:161], v[160:161], v[238:239] op_sel_hi:[1,0]
	v_pk_mul_f32 v[146:147], v[146:147], v[238:239] op_sel:[0,1] op_sel_hi:[1,1]
	v_pk_mul_f32 v[148:149], v[148:149], v[238:239] op_sel:[0,1] op_sel_hi:[1,1]
	v_pk_mul_f32 v[150:151], v[150:151], v[238:239] op_sel:[0,1] op_sel_hi:[1,1]
	v_pk_mul_f32 v[152:153], v[152:153], v[238:239] op_sel:[0,1] op_sel_hi:[1,1]
	v_pk_mul_f32 v[154:155], v[154:155], v[238:239] op_sel:[0,1] op_sel_hi:[1,1]
	v_pk_mul_f32 v[156:157], v[156:157], v[238:239] op_sel:[0,1] op_sel_hi:[1,1]
	v_pk_mul_f32 v[158:159], v[158:159], v[238:239] op_sel:[0,1] op_sel_hi:[1,1]
	v_pk_mul_f32 v[160:161], v[160:161], v[238:239] op_sel:[0,1] op_sel_hi:[1,1]
	v_pk_fma_f32 v[146:147], v[188:189], v[146:147], v[204:205]
	v_pk_fma_f32 v[148:149], v[190:191], v[148:149], v[206:207]
	v_pk_fma_f32 v[150:151], v[192:193], v[150:151], v[208:209]
	v_pk_fma_f32 v[152:153], v[194:195], v[152:153], v[210:211]
	v_pk_fma_f32 v[154:155], v[196:197], v[154:155], v[212:213]
	v_pk_fma_f32 v[156:157], v[198:199], v[156:157], v[214:215]
	v_pk_fma_f32 v[158:159], v[200:201], v[158:159], v[216:217]
	v_pk_fma_f32 v[160:161], v[202:203], v[160:161], v[218:219]
	v_pk_fma_f32 v[60:61], v[146:147], s[90:91], v[60:61] op_sel_hi:[1,0,1]
	v_pk_fma_f32 v[62:63], v[148:149], s[90:91], v[62:63] op_sel_hi:[1,0,1]
	v_pk_fma_f32 v[56:57], v[150:151], s[90:91], v[56:57] op_sel_hi:[1,0,1]
	v_pk_fma_f32 v[58:59], v[152:153], s[90:91], v[58:59] op_sel_hi:[1,0,1]
	v_pk_fma_f32 v[52:53], v[154:155], s[90:91], v[52:53] op_sel_hi:[1,0,1]
	v_pk_fma_f32 v[54:55], v[156:157], s[90:91], v[54:55] op_sel_hi:[1,0,1]
	v_pk_fma_f32 v[48:49], v[158:159], s[90:91], v[48:49] op_sel_hi:[1,0,1]
	v_pk_fma_f32 v[50:51], v[160:161], s[90:91], v[50:51] op_sel_hi:[1,0,1]
	global_store_dwordx4 v242, v[60:63], s[48:49]
	global_store_dwordx4 v242, v[56:59], s[48:49] offset:16
	global_store_dwordx4 v242, v[52:55], s[48:49] offset:512
	global_store_dwordx4 v242, v[48:51], s[48:49] offset:528
	s_waitcnt vmcnt(30)
	v_pk_add_f32 v[172:173], v[172:173], v[240:241] op_sel_hi:[1,0]
	v_pk_add_f32 v[174:175], v[174:175], v[240:241] op_sel_hi:[1,0]
	v_pk_add_f32 v[176:177], v[176:177], v[240:241] op_sel_hi:[1,0]
	v_pk_add_f32 v[178:179], v[178:179], v[240:241] op_sel_hi:[1,0]
	v_pk_add_f32 v[180:181], v[180:181], v[240:241] op_sel_hi:[1,0]
	v_pk_add_f32 v[182:183], v[182:183], v[240:241] op_sel_hi:[1,0]
	v_pk_add_f32 v[234:235], v[234:235], v[240:241] op_sel_hi:[1,0]
	v_pk_add_f32 v[236:237], v[236:237], v[240:241] op_sel_hi:[1,0]
	v_pk_mul_f32 v[172:173], v[172:173], v[240:241] op_sel:[0,1] op_sel_hi:[1,1]
	v_pk_mul_f32 v[174:175], v[174:175], v[240:241] op_sel:[0,1] op_sel_hi:[1,1]
	v_pk_mul_f32 v[176:177], v[176:177], v[240:241] op_sel:[0,1] op_sel_hi:[1,1]
	v_pk_mul_f32 v[178:179], v[178:179], v[240:241] op_sel:[0,1] op_sel_hi:[1,1]
	v_pk_mul_f32 v[180:181], v[180:181], v[240:241] op_sel:[0,1] op_sel_hi:[1,1]
	v_pk_mul_f32 v[182:183], v[182:183], v[240:241] op_sel:[0,1] op_sel_hi:[1,1]
	v_pk_mul_f32 v[234:235], v[234:235], v[240:241] op_sel:[0,1] op_sel_hi:[1,1]
	v_pk_mul_f32 v[236:237], v[236:237], v[240:241] op_sel:[0,1] op_sel_hi:[1,1]
	v_pk_fma_f32 v[172:173], v[188:189], v[172:173], v[204:205]
	v_pk_fma_f32 v[174:175], v[190:191], v[174:175], v[206:207]
	v_pk_fma_f32 v[176:177], v[192:193], v[176:177], v[208:209]
	v_pk_fma_f32 v[178:179], v[194:195], v[178:179], v[210:211]
	v_pk_fma_f32 v[180:181], v[196:197], v[180:181], v[212:213]
	v_pk_fma_f32 v[182:183], v[198:199], v[182:183], v[214:215]
	v_pk_fma_f32 v[234:235], v[200:201], v[234:235], v[216:217]
	v_pk_fma_f32 v[236:237], v[202:203], v[236:237], v[218:219]
	v_pk_fma_f32 v[44:45], v[172:173], s[90:91], v[44:45] op_sel_hi:[1,0,1]
	v_pk_fma_f32 v[46:47], v[174:175], s[90:91], v[46:47] op_sel_hi:[1,0,1]
	v_pk_fma_f32 v[40:41], v[176:177], s[90:91], v[40:41] op_sel_hi:[1,0,1]
	v_pk_fma_f32 v[42:43], v[178:179], s[90:91], v[42:43] op_sel_hi:[1,0,1]
	v_pk_fma_f32 v[36:37], v[180:181], s[90:91], v[36:37] op_sel_hi:[1,0,1]
	v_pk_fma_f32 v[38:39], v[182:183], s[90:91], v[38:39] op_sel_hi:[1,0,1]
	v_pk_fma_f32 v[32:33], v[234:235], s[90:91], v[32:33] op_sel_hi:[1,0,1]
	v_pk_fma_f32 v[34:35], v[236:237], s[90:91], v[34:35] op_sel_hi:[1,0,1]
	global_store_dwordx4 v242, v[44:47], s[50:51]
	global_store_dwordx4 v242, v[40:43], s[50:51] offset:16
	global_store_dwordx4 v242, v[36:39], s[50:51] offset:512
	global_store_dwordx4 v242, v[32:35], s[50:51] offset:528
	s_waitcnt vmcnt(17)
; template <class Epi>
; __device__ __forceinline__ void gemm_phase(LAS unsigned char* lds, const Gemm g, const StaticOrder& S, const Epi& E, int wv0) {
;     ...
;     cur = nxt; cA = nA; cB = nB; ++ui;
;   __device__ __forceinline__ void emit(const EpiPre& q0, int row, int col, f32x4 a, f32x4 b, const f32x4 (&hb)[2][2], const float (&hs)[2][4], int ai_, int m_, int bj_) const {
;     ...
;     } else if (MODE == E_RES) {
;       const f32x4 r0 = q.a0, r1 = q.a1;
;       float* o = (float*)e.out + (size_t)row * DM + col;
;       *(f32x4*)o = (f32x4){ALPHA * r0[0] + v[0], ALPHA * r0[1] + v[1], ALPHA * r0[2] + v[2], ALPHA * r0[3] + v[3]};
;       *(f32x4*)(o + 4) = (f32x4){ALPHA * r1[0] + v[4], ALPHA * r1[1] + v[5], ALPHA * r1[2] + v[6], ALPHA * r1[3] + v[7]};
; __device__ __forceinline__ void ln_phase(const float* in, float* outf, bf16_t* outb, const float* g, const float* b, int wv0) {
;     ...
;     for (int i = 0; i < 8; ++i) { v[i] -= mu; sq += v[i][0] * v[i][0] + v[i][1] * v[i][1] + v[i][2] * v[i][2] + v[i][3] * v[i][3]; }
;     sq = wave_sum(sq); const float rstd = __builtin_amdgcn_rsqf(sq * (1.0f / 2048.0f) + EPS);
; #pragma unroll
;     for (int i = 0; i < 8; ++i) {
;       const f32x4 y = v[i] * rstd * gg[i] + bb[i];
	v_pk_add_f32 v[126:127], v[126:127], v[92:93] op_sel_hi:[1,0]
	v_pk_add_f32 v[128:129], v[128:129], v[92:93] op_sel_hi:[1,0]
	v_pk_add_f32 v[122:123], v[122:123], v[92:93] op_sel_hi:[1,0]
	v_pk_add_f32 v[124:125], v[124:125], v[92:93] op_sel_hi:[1,0]
	v_pk_add_f32 v[110:111], v[110:111], v[92:93] op_sel_hi:[1,0]
	v_pk_add_f32 v[112:113], v[112:113], v[92:93] op_sel_hi:[1,0]
	v_pk_add_f32 v[106:107], v[106:107], v[92:93] op_sel_hi:[1,0]
	v_pk_add_f32 v[108:109], v[108:109], v[92:93] op_sel_hi:[1,0]
	v_pk_mul_f32 v[126:127], v[126:127], v[92:93] op_sel:[0,1] op_sel_hi:[1,1]
	v_pk_mul_f32 v[128:129], v[128:129], v[92:93] op_sel:[0,1] op_sel_hi:[1,1]
	v_pk_mul_f32 v[122:123], v[122:123], v[92:93] op_sel:[0,1] op_sel_hi:[1,1]
	v_pk_mul_f32 v[124:125], v[124:125], v[92:93] op_sel:[0,1] op_sel_hi:[1,1]
	v_pk_mul_f32 v[110:111], v[110:111], v[92:93] op_sel:[0,1] op_sel_hi:[1,1]
	v_pk_mul_f32 v[112:113], v[112:113], v[92:93] op_sel:[0,1] op_sel_hi:[1,1]
	v_pk_mul_f32 v[106:107], v[106:107], v[92:93] op_sel:[0,1] op_sel_hi:[1,1]
	v_pk_mul_f32 v[108:109], v[108:109], v[92:93] op_sel:[0,1] op_sel_hi:[1,1]
	v_pk_fma_f32 v[126:127], v[188:189], v[126:127], v[204:205]
	v_pk_fma_f32 v[128:129], v[190:191], v[128:129], v[206:207]
	v_pk_fma_f32 v[122:123], v[192:193], v[122:123], v[208:209]
	v_pk_fma_f32 v[124:125], v[194:195], v[124:125], v[210:211]
	v_pk_fma_f32 v[110:111], v[196:197], v[110:111], v[212:213]
	v_pk_fma_f32 v[112:113], v[198:199], v[112:113], v[214:215]
	v_pk_fma_f32 v[106:107], v[200:201], v[106:107], v[216:217]
	v_pk_fma_f32 v[108:109], v[202:203], v[108:109], v[218:219]
	v_pk_fma_f32 v[28:29], v[126:127], s[90:91], v[28:29] op_sel_hi:[1,0,1]
	v_pk_fma_f32 v[30:31], v[128:129], s[90:91], v[30:31] op_sel_hi:[1,0,1]
	v_pk_fma_f32 v[24:25], v[122:123], s[90:91], v[24:25] op_sel_hi:[1,0,1]
	v_pk_fma_f32 v[26:27], v[124:125], s[90:91], v[26:27] op_sel_hi:[1,0,1]
	v_pk_fma_f32 v[16:17], v[110:111], s[90:91], v[16:17] op_sel_hi:[1,0,1]
	v_pk_fma_f32 v[18:19], v[112:113], s[90:91], v[18:19] op_sel_hi:[1,0,1]
	v_pk_fma_f32 v[12:13], v[106:107], s[90:91], v[12:13] op_sel_hi:[1,0,1]
	v_pk_fma_f32 v[14:15], v[108:109], s[90:91], v[14:15] op_sel_hi:[1,0,1]
	global_store_dwordx4 v242, v[28:31], s[20:21]
	global_store_dwordx4 v242, v[24:27], s[20:21] offset:16
	global_store_dwordx4 v242, v[16:19], s[20:21] offset:512
	global_store_dwordx4 v242, v[12:15], s[20:21] offset:528
	s_waitcnt vmcnt(16)
	v_pk_add_f32 v[118:119], v[118:119], v[88:89] op_sel_hi:[1,0]
	v_pk_add_f32 v[120:121], v[120:121], v[88:89] op_sel_hi:[1,0]
	v_pk_add_f32 v[114:115], v[114:115], v[88:89] op_sel_hi:[1,0]
	v_pk_add_f32 v[116:117], v[116:117], v[88:89] op_sel_hi:[1,0]
	v_pk_add_f32 v[102:103], v[102:103], v[88:89] op_sel_hi:[1,0]
	v_pk_add_f32 v[104:105], v[104:105], v[88:89] op_sel_hi:[1,0]
	v_pk_add_f32 v[98:99], v[98:99], v[88:89] op_sel_hi:[1,0]
	v_pk_add_f32 v[100:101], v[100:101], v[88:89] op_sel_hi:[1,0]
	v_pk_mul_f32 v[118:119], v[118:119], v[88:89] op_sel:[0,1] op_sel_hi:[1,1]
	v_pk_mul_f32 v[120:121], v[120:121], v[88:89] op_sel:[0,1] op_sel_hi:[1,1]
	v_pk_mul_f32 v[114:115], v[114:115], v[88:89] op_sel:[0,1] op_sel_hi:[1,1]
	v_pk_mul_f32 v[116:117], v[116:117], v[88:89] op_sel:[0,1] op_sel_hi:[1,1]
	v_pk_mul_f32 v[102:103], v[102:103], v[88:89] op_sel:[0,1] op_sel_hi:[1,1]
	v_pk_mul_f32 v[104:105], v[104:105], v[88:89] op_sel:[0,1] op_sel_hi:[1,1]
	v_pk_mul_f32 v[98:99], v[98:99], v[88:89] op_sel:[0,1] op_sel_hi:[1,1]
	v_pk_mul_f32 v[100:101], v[100:101], v[88:89] op_sel:[0,1] op_sel_hi:[1,1]
	v_pk_fma_f32 v[118:119], v[188:189], v[118:119], v[204:205]
	v_pk_fma_f32 v[120:121], v[190:191], v[120:121], v[206:207]
	v_pk_fma_f32 v[114:115], v[192:193], v[114:115], v[208:209]
	v_pk_fma_f32 v[116:117], v[194:195], v[116:117], v[210:211]
	v_pk_fma_f32 v[102:103], v[196:197], v[102:103], v[212:213]
	v_pk_fma_f32 v[104:105], v[198:199], v[104:105], v[214:215]
	v_pk_fma_f32 v[98:99], v[200:201], v[98:99], v[216:217]
	v_pk_fma_f32 v[100:101], v[202:203], v[100:101], v[218:219]
	v_pk_fma_f32 v[20:21], v[118:119], s[90:91], v[20:21] op_sel_hi:[1,0,1]
	v_pk_fma_f32 v[22:23], v[120:121], s[90:91], v[22:23] op_sel_hi:[1,0,1]
	v_pk_fma_f32 v[8:9], v[114:115], s[90:91], v[8:9] op_sel_hi:[1,0,1]
	v_pk_fma_f32 v[10:11], v[116:117], s[90:91], v[10:11] op_sel_hi:[1,0,1]
	v_pk_fma_f32 v[4:5], v[102:103], s[90:91], v[4:5] op_sel_hi:[1,0,1]
	v_pk_fma_f32 v[6:7], v[104:105], s[90:91], v[6:7] op_sel_hi:[1,0,1]
	v_pk_fma_f32 v[0:1], v[98:99], s[90:91], v[0:1] op_sel_hi:[1,0,1]
	v_pk_fma_f32 v[2:3], v[100:101], s[90:91], v[2:3] op_sel_hi:[1,0,1]
	global_store_dwordx4 v242, v[20:23], s[22:23]
	global_store_dwordx4 v242, v[8:11], s[22:23] offset:16
	global_store_dwordx4 v242, v[4:7], s[22:23] offset:512
	global_store_dwordx4 v242, v[0:3], s[22:23] offset:528
	s_mov_b32 s18, s12
	s_mov_b64 s[22:23], s[16:17]
	s_mov_b64 s[20:21], s[14:15]
	s_and_b64 vcc, exec, s[2:3]
	s_mov_b32 s1, s10
	s_branch .Lwo_join
;   __device__ __forceinline__ void emit(const EpiPre& q0, int row, int col, f32x4 a, f32x4 b, const f32x4 (&hb)[2][2], const float (&hs)[2][4], int ai_, int m_, int bj_) const {
;     ...
;     } else if (MODE == E_RES) {
;       const f32x4 r0 = q.a0, r1 = q.a1;
;       float* o = (float*)e.out + (size_t)row * DM + col;
;       *(f32x4*)o = (f32x4){ALPHA * r0[0] + v[0], ALPHA * r0[1] + v[1], ALPHA * r0[2] + v[2], ALPHA * r0[3] + v[3]};
;       *(f32x4*)(o + 4) = (f32x4){ALPHA * r1[0] + v[4], ALPHA * r1[1] + v[5], ALPHA * r1[2] + v[6], ALPHA * r1[3] + v[7]};
.Lwo_plain:
	v_lshl_add_u32 v172, s18, 8, v184
	v_lshl_or_b32 v180, s1, 8, v186
	v_lshlrev_b32_e32 v172, 13, v172
	v_lshl_add_u32 v172, v180, 2, v172
	global_load_dwordx4 v[130:133], v172, s[8:9]
	global_load_dwordx4 v[134:137], v172, s[8:9] offset:16
	global_load_dwordx4 v[138:141], v172, s[8:9] offset:512
	global_load_dwordx4 v[142:145], v172, s[8:9] offset:528
	v_add_u32_e32 v173, 0x20000, v172
	global_load_dwordx4 v[146:149], v173, s[8:9]
	global_load_dwordx4 v[150:153], v173, s[8:9] offset:16
	global_load_dwordx4 v[154:157], v173, s[8:9] offset:512
	global_load_dwordx4 v[158:161], v173, s[8:9] offset:528
	v_add_u32_e32 v174, 0x40000, v172
	global_load_dwordx4 v[188:191], v174, s[8:9]
	global_load_dwordx4 v[192:195], v174, s[8:9] offset:16
	global_load_dwordx4 v[196:199], v174, s[8:9] offset:512
	global_load_dwordx4 v[200:203], v174, s[8:9] offset:528
	v_add_u32_e32 v175, 0x60000, v172
	global_load_dwordx4 v[204:207], v175, s[8:9]
	global_load_dwordx4 v[208:211], v175, s[8:9] offset:16
	global_load_dwordx4 v[212:215], v175, s[8:9] offset:512
	global_load_dwordx4 v[216:219], v175, s[8:9] offset:528
	v_add_u32_e32 v176, 0x100000, v172
	v_add_u32_e32 v177, 0x120000, v172
	v_add_u32_e32 v178, 0x140000, v172
	v_add_u32_e32 v179, 0x160000, v172
	s_waitcnt vmcnt(12)
	v_pk_fma_f32 v[126:127], v[130:131], s[90:91], v[126:127] op_sel_hi:[1,0,1]
	v_pk_fma_f32 v[128:129], v[132:133], s[90:91], v[128:129] op_sel_hi:[1,0,1]
	v_pk_fma_f32 v[122:123], v[134:135], s[90:91], v[122:123] op_sel_hi:[1,0,1]
	v_pk_fma_f32 v[124:125], v[136:137], s[90:91], v[124:125] op_sel_hi:[1,0,1]
	v_pk_fma_f32 v[110:111], v[138:139], s[90:91], v[110:111] op_sel_hi:[1,0,1]
	v_pk_fma_f32 v[112:113], v[140:141], s[90:91], v[112:113] op_sel_hi:[1,0,1]
	v_pk_fma_f32 v[106:107], v[142:143], s[90:91], v[106:107] op_sel_hi:[1,0,1]
	v_pk_fma_f32 v[108:109], v[144:145], s[90:91], v[108:109] op_sel_hi:[1,0,1]
	global_load_dwordx4 v[130:133], v176, s[8:9]
	global_load_dwordx4 v[134:137], v176, s[8:9] offset:16
	global_load_dwordx4 v[138:141], v176, s[8:9] offset:512
	global_load_dwordx4 v[142:145], v176, s[8:9] offset:528
	s_waitcnt vmcnt(12)
	v_pk_fma_f32 v[118:119], v[146:147], s[90:91], v[118:119] op_sel_hi:[1,0,1]
	v_pk_fma_f32 v[120:121], v[148:149], s[90:91], v[120:121] op_sel_hi:[1,0,1]
	v_pk_fma_f32 v[114:115], v[150:151], s[90:91], v[114:115] op_sel_hi:[1,0,1]
	v_pk_fma_f32 v[116:117], v[152:153], s[90:91], v[116:117] op_sel_hi:[1,0,1]
	v_pk_fma_f32 v[102:103], v[154:155], s[90:91], v[102:103] op_sel_hi:[1,0,1]
	v_pk_fma_f32 v[104:105], v[156:157], s[90:91], v[104:105] op_sel_hi:[1,0,1]
	v_pk_fma_f32 v[98:99], v[158:159], s[90:91], v[98:99] op_sel_hi:[1,0,1]
	v_pk_fma_f32 v[100:101], v[160:161], s[90:91], v[100:101] op_sel_hi:[1,0,1]
	global_load_dwordx4 v[146:149], v177, s[8:9]
	global_load_dwordx4 v[150:153], v177, s[8:9] offset:16
	global_load_dwordx4 v[154:157], v177, s[8:9] offset:512
	global_load_dwordx4 v[158:161], v177, s[8:9] offset:528
	s_waitcnt vmcnt(12)
	v_pk_fma_f32 v[92:93], v[188:189], s[90:91], v[92:93] op_sel_hi:[1,0,1]
	v_pk_fma_f32 v[94:95], v[190:191], s[90:91], v[94:95] op_sel_hi:[1,0,1]
	v_pk_fma_f32 v[88:89], v[192:193], s[90:91], v[88:89] op_sel_hi:[1,0,1]
	v_pk_fma_f32 v[90:91], v[194:195], s[90:91], v[90:91] op_sel_hi:[1,0,1]
	v_pk_fma_f32 v[80:81], v[196:197], s[90:91], v[80:81] op_sel_hi:[1,0,1]
	v_pk_fma_f32 v[82:83], v[198:199], s[90:91], v[82:83] op_sel_hi:[1,0,1]
	v_pk_fma_f32 v[72:73], v[200:201], s[90:91], v[72:73] op_sel_hi:[1,0,1]
	v_pk_fma_f32 v[74:75], v[202:203], s[90:91], v[74:75] op_sel_hi:[1,0,1]
	global_load_dwordx4 v[188:191], v178, s[8:9]
	global_load_dwordx4 v[192:195], v178, s[8:9] offset:16
	global_load_dwordx4 v[196:199], v178, s[8:9] offset:512
	global_load_dwordx4 v[200:203], v178, s[8:9] offset:528
	s_waitcnt vmcnt(12)
; #define PG8_WAIT_V(n) asm volatile("s_waitcnt vmcnt(" #n ")" ::: "memory")
; #define PG8_BAR __builtin_amdgcn_s_barrier()
; template <class Epi>
; __device__ __forceinline__ void gemm_phase(LAS unsigned char* lds, const Gemm g, const StaticOrder& S, const Epi& E, int wv0) {
;     ...
;     if (!has_next) break;
; #pragma unroll
;     for (int a = 0; a < 2; ++a)
; #pragma unroll
;       for (int b = 0; b < 2; ++b)
; #pragma unroll
;         for (int m = 0; m < 4; ++m)
; #pragma unroll
;           for (int n = 0; n < 2; ++n) acc[a][b][m][n] = (f32x4){0.f, 0.f, 0.f, 0.f};
;     cur = nxt; cA = nA; cB = nB; ++ui;
;   }
;   PG8_WAIT_V(0);
;   if (wr == 0) PG8_BAR;
;   PG8_BAR;
;   __device__ __forceinline__ void emit(const EpiPre& q0, int row, int col, f32x4 a, f32x4 b, const f32x4 (&hb)[2][2], const float (&hs)[2][4], int ai_, int m_, int bj_) const {
;     ...
;     } else if (MODE == E_RES) {
;       const f32x4 r0 = q.a0, r1 = q.a1;
;       float* o = (float*)e.out + (size_t)row * DM + col;
;       *(f32x4*)o = (f32x4){ALPHA * r0[0] + v[0], ALPHA * r0[1] + v[1], ALPHA * r0[2] + v[2], ALPHA * r0[3] + v[3]};
;       *(f32x4*)(o + 4) = (f32x4){ALPHA * r1[0] + v[4], ALPHA * r1[1] + v[5], ALPHA * r1[2] + v[6], ALPHA * r1[3] + v[7]};
	v_pk_fma_f32 v[84:85], v[204:205], s[90:91], v[84:85] op_sel_hi:[1,0,1]
	v_pk_fma_f32 v[86:87], v[206:207], s[90:91], v[86:87] op_sel_hi:[1,0,1]
	v_pk_fma_f32 v[76:77], v[208:209], s[90:91], v[76:77] op_sel_hi:[1,0,1]
	v_pk_fma_f32 v[78:79], v[210:211], s[90:91], v[78:79] op_sel_hi:[1,0,1]
	v_pk_fma_f32 v[68:69], v[212:213], s[90:91], v[68:69] op_sel_hi:[1,0,1]
	v_pk_fma_f32 v[70:71], v[214:215], s[90:91], v[70:71] op_sel_hi:[1,0,1]
	v_pk_fma_f32 v[64:65], v[216:217], s[90:91], v[64:65] op_sel_hi:[1,0,1]
	v_pk_fma_f32 v[66:67], v[218:219], s[90:91], v[66:67] op_sel_hi:[1,0,1]
	global_load_dwordx4 v[204:207], v179, s[8:9]
	global_load_dwordx4 v[208:211], v179, s[8:9] offset:16
	global_load_dwordx4 v[212:215], v179, s[8:9] offset:512
	global_load_dwordx4 v[216:219], v179, s[8:9] offset:528
	global_store_dwordx4 v172, v[126:129], s[6:7]
	global_store_dwordx4 v172, v[122:125], s[6:7] offset:16
	global_store_dwordx4 v172, v[110:113], s[6:7] offset:512
	global_store_dwordx4 v172, v[106:109], s[6:7] offset:528
	global_store_dwordx4 v173, v[118:121], s[6:7]
	global_store_dwordx4 v173, v[114:117], s[6:7] offset:16
	global_store_dwordx4 v173, v[102:105], s[6:7] offset:512
	global_store_dwordx4 v173, v[98:101], s[6:7] offset:528
	global_store_dwordx4 v174, v[92:95], s[6:7]
	global_store_dwordx4 v174, v[88:91], s[6:7] offset:16
	global_store_dwordx4 v174, v[80:83], s[6:7] offset:512
	global_store_dwordx4 v174, v[72:75], s[6:7] offset:528
	global_store_dwordx4 v175, v[84:87], s[6:7]
	global_store_dwordx4 v175, v[76:79], s[6:7] offset:16
	global_store_dwordx4 v175, v[68:71], s[6:7] offset:512
	global_store_dwordx4 v175, v[64:67], s[6:7] offset:528
	s_waitcnt vmcnt(28)
	v_pk_fma_f32 v[60:61], v[130:131], s[90:91], v[60:61] op_sel_hi:[1,0,1]
	v_pk_fma_f32 v[62:63], v[132:133], s[90:91], v[62:63] op_sel_hi:[1,0,1]
	v_pk_fma_f32 v[56:57], v[134:135], s[90:91], v[56:57] op_sel_hi:[1,0,1]
	v_pk_fma_f32 v[58:59], v[136:137], s[90:91], v[58:59] op_sel_hi:[1,0,1]
	v_pk_fma_f32 v[52:53], v[138:139], s[90:91], v[52:53] op_sel_hi:[1,0,1]
	v_pk_fma_f32 v[54:55], v[140:141], s[90:91], v[54:55] op_sel_hi:[1,0,1]
	v_pk_fma_f32 v[48:49], v[142:143], s[90:91], v[48:49] op_sel_hi:[1,0,1]
	v_pk_fma_f32 v[50:51], v[144:145], s[90:91], v[50:51] op_sel_hi:[1,0,1]
	global_store_dwordx4 v176, v[60:63], s[6:7]
	global_store_dwordx4 v176, v[56:59], s[6:7] offset:16
	global_store_dwordx4 v176, v[52:55], s[6:7] offset:512
	global_store_dwordx4 v176, v[48:51], s[6:7] offset:528
	s_waitcnt vmcnt(28)
	v_pk_fma_f32 v[44:45], v[146:147], s[90:91], v[44:45] op_sel_hi:[1,0,1]
	v_pk_fma_f32 v[46:47], v[148:149], s[90:91], v[46:47] op_sel_hi:[1,0,1]
	v_pk_fma_f32 v[40:41], v[150:151], s[90:91], v[40:41] op_sel_hi:[1,0,1]
	v_pk_fma_f32 v[42:43], v[152:153], s[90:91], v[42:43] op_sel_hi:[1,0,1]
	v_pk_fma_f32 v[36:37], v[154:155], s[90:91], v[36:37] op_sel_hi:[1,0,1]
	v_pk_fma_f32 v[38:39], v[156:157], s[90:91], v[38:39] op_sel_hi:[1,0,1]
	v_pk_fma_f32 v[32:33], v[158:159], s[90:91], v[32:33] op_sel_hi:[1,0,1]
	v_pk_fma_f32 v[34:35], v[160:161], s[90:91], v[34:35] op_sel_hi:[1,0,1]
	global_store_dwordx4 v177, v[44:47], s[6:7]
	global_store_dwordx4 v177, v[40:43], s[6:7] offset:16
	global_store_dwordx4 v177, v[36:39], s[6:7] offset:512
	global_store_dwordx4 v177, v[32:35], s[6:7] offset:528
	s_waitcnt vmcnt(28)
	v_pk_fma_f32 v[28:29], v[188:189], s[90:91], v[28:29] op_sel_hi:[1,0,1]
	v_pk_fma_f32 v[30:31], v[190:191], s[90:91], v[30:31] op_sel_hi:[1,0,1]
	v_pk_fma_f32 v[24:25], v[192:193], s[90:91], v[24:25] op_sel_hi:[1,0,1]
	v_pk_fma_f32 v[26:27], v[194:195], s[90:91], v[26:27] op_sel_hi:[1,0,1]
	v_pk_fma_f32 v[16:17], v[196:197], s[90:91], v[16:17] op_sel_hi:[1,0,1]
	v_pk_fma_f32 v[18:19], v[198:199], s[90:91], v[18:19] op_sel_hi:[1,0,1]
	v_pk_fma_f32 v[12:13], v[200:201], s[90:91], v[12:13] op_sel_hi:[1,0,1]
	v_pk_fma_f32 v[14:15], v[202:203], s[90:91], v[14:15] op_sel_hi:[1,0,1]
	global_store_dwordx4 v178, v[28:31], s[6:7]
	global_store_dwordx4 v178, v[24:27], s[6:7] offset:16
	global_store_dwordx4 v178, v[16:19], s[6:7] offset:512
	global_store_dwordx4 v178, v[12:15], s[6:7] offset:528
	s_waitcnt vmcnt(28)
	v_pk_fma_f32 v[20:21], v[204:205], s[90:91], v[20:21] op_sel_hi:[1,0,1]
	v_pk_fma_f32 v[22:23], v[206:207], s[90:91], v[22:23] op_sel_hi:[1,0,1]
	v_pk_fma_f32 v[8:9], v[208:209], s[90:91], v[8:9] op_sel_hi:[1,0,1]
	v_pk_fma_f32 v[10:11], v[210:211], s[90:91], v[10:11] op_sel_hi:[1,0,1]
	v_pk_fma_f32 v[4:5], v[212:213], s[90:91], v[4:5] op_sel_hi:[1,0,1]
	v_pk_fma_f32 v[6:7], v[214:215], s[90:91], v[6:7] op_sel_hi:[1,0,1]
	v_pk_fma_f32 v[0:1], v[216:217], s[90:91], v[0:1] op_sel_hi:[1,0,1]
	v_pk_fma_f32 v[2:3], v[218:219], s[90:91], v[2:3] op_sel_hi:[1,0,1]
	global_store_dwordx4 v179, v[20:23], s[6:7]
	global_store_dwordx4 v179, v[8:11], s[6:7] offset:16
	global_store_dwordx4 v179, v[4:7], s[6:7] offset:512
	global_store_dwordx4 v179, v[0:3], s[6:7] offset:528
	s_mov_b32 s18, s12
	s_mov_b64 s[22:23], s[16:17]
	s_mov_b64 s[20:21], s[14:15]
	s_and_b64 vcc, exec, s[2:3]
	s_mov_b32 s1, s10
.Lwo_join:
	s_cbranch_vccz .LBB0_1093
	s_waitcnt vmcnt(0)
	s_cmpk_gt_u32 s29, 0xff
	s_cbranch_scc1 .LBB0_1104
	s_barrier

; __device__ __forceinline__ int otid(int wv0) { int t = (wv0 << 6) | olane(); asm volatile("" : "+v"(t)); return t; }
; __device__ __forceinline__ int obid() { int b = blockIdx.x; asm volatile("" : "+s"(b)); return b; }
; __device__ __forceinline__ int ogrid() { int g = gridDim.x; asm volatile("" : "+s"(g)); return g; }
; __device__ __forceinline__ void ln_phase(const float* in, float* outf, bf16_t* outb, const float* g, const float* b, int wv0) {
;   const int tid_ = otid(wv0); const int lane = tid_ & 63, wv = obid() * 8 + (tid_ >> 6), nwv = ogrid() * 8;
;   f32x4 gg[8], bb[8];
; #pragma unroll
;   for (int i = 0; i < 8; ++i) { gg[i] = ((const f32x4*)g)[i * 64 + lane]; bb[i] = ((const f32x4*)b)[i * 64 + lane]; }
;   f32x4 vn[8];
;   if (wv < NTOK) { const f32x4* ir = (const f32x4*)(in + (size_t)wv * DM);
; #pragma unroll
;     for (int i = 0; i < 8; ++i) vn[i] = ir[i * 64 + lane]; }
;   for (int row = wv; row < NTOK; row += nwv) {
;     f32x4 v[8]; float s = 0.f;
; #pragma unroll
;     for (int i = 0; i < 8; ++i) v[i] = vn[i];
;     if (row + nwv < NTOK) { const f32x4* ir = (const f32x4*)(in + (size_t)(row + nwv) * DM);
; #pragma unroll
;       for (int i = 0; i < 8; ++i) vn[i] = ir[i * 64 + lane]; }
; #pragma unroll
;     for (int i = 0; i < 8; ++i) s += v[i][0] + v[i][1] + v[i][2] + v[i][3];
;     s = wave_sum(s); const float mu = s * (1.0f / 2048.0f);
.LBB0_1490:
	s_mov_b32 s0, -1
	s_lshl_b32 s22, s53, 6
	v_mbcnt_lo_u32_b32 v0, s0, 0
	v_mbcnt_hi_u32_b32 v0, s0, v0
	v_or_b32_e32 v0, s22, v0
	s_mov_b32 s1, s82
	v_ashrrev_i32_e32 v1, 6, v0
	s_mov_b32 s0, s60
	v_lshl_add_u32 v130, s1, 3, v1
	v_cmp_gt_i32_e32 vcc, s61, v130
	s_and_saveexec_b64 s[10:11], vcc
	s_cbranch_execz .LBB0_1511
	s_waitcnt lgkmcnt(0)
	s_lshl_b32 s0, s66, 13
	s_add_u32 s16, s4, s0
	s_addc_u32 s17, s5, 0
	s_add_u32 s14, s6, s0
	s_addc_u32 s15, s7, 0
	s_cmp_eq_u32 s66, 1
	s_cbranch_scc1 .Lln2_last
	s_load_dwordx2 s[0:1], s[54:55], 0xc8
	s_waitcnt lgkmcnt(0)
	s_add_u32 s0, s0, 0x4000000
	s_addc_u32 s1, s1, 0
	v_mbcnt_lo_u32_b32 v243, -1, 0
	v_mbcnt_hi_u32_b32 v243, -1, v243
	v_lshlrev_b32_e32 v240, 5, v243
	v_add_u32_e32 v241, 0x1000, v240
	v_lshlrev_b32_e32 v242, 4, v243
	s_lshl_b32 s20, s82, 3
	s_add_u32 s20, s20, s53
	s_lshl_b32 s21, s60, 3
	global_load_dwordx4 v[0:3], v240, s[16:17]
	global_load_dwordx4 v[4:7], v240, s[16:17] offset:16
	global_load_dwordx4 v[8:11], v240, s[16:17] offset:2048
	global_load_dwordx4 v[12:15], v240, s[16:17] offset:2064
	global_load_dwordx4 v[16:19], v241, s[16:17]
	global_load_dwordx4 v[20:23], v241, s[16:17] offset:16
	global_load_dwordx4 v[24:27], v241, s[16:17] offset:2048
	global_load_dwordx4 v[28:31], v241, s[16:17] offset:2064
	global_load_dwordx4 v[32:35], v240, s[14:15]
	global_load_dwordx4 v[36:39], v240, s[14:15] offset:16
	global_load_dwordx4 v[40:43], v240, s[14:15] offset:2048
	global_load_dwordx4 v[44:47], v240, s[14:15] offset:2064
	global_load_dwordx4 v[48:51], v241, s[14:15]
	global_load_dwordx4 v[52:55], v241, s[14:15] offset:16
	global_load_dwordx4 v[56:59], v241, s[14:15] offset:2048
	global_load_dwordx4 v[60:63], v241, s[14:15] offset:2064
	s_mov_b32 s23, s20
	s_min_u32 s23, s23, 0x3fff
	s_lshl_b32 s23, s23, 13
	s_add_u32 s24, s12, s23
	s_addc_u32 s25, s13, 0
	global_load_dwordx4 v[64:67], v240, s[24:25]
	global_load_dwordx4 v[68:71], v240, s[24:25] offset:16
	global_load_dwordx4 v[72:75], v240, s[24:25] offset:2048
	global_load_dwordx4 v[76:79], v240, s[24:25] offset:2064
	global_load_dwordx4 v[80:83], v241, s[24:25]
	global_load_dwordx4 v[84:87], v241, s[24:25] offset:16
	global_load_dwordx4 v[88:91], v241, s[24:25] offset:2048
	global_load_dwordx4 v[92:95], v241, s[24:25] offset:2064
	s_mul_i32 s23, s21, 1
	s_add_u32 s23, s20, s23
	s_min_u32 s23, s23, 0x3fff
	s_lshl_b32 s23, s23, 13
	s_add_u32 s24, s12, s23
	s_addc_u32 s25, s13, 0
	global_load_dwordx4 v[96:99], v240, s[24:25]
	global_load_dwordx4 v[100:103], v240, s[24:25] offset:16
	global_load_dwordx4 v[104:107], v240, s[24:25] offset:2048
	global_load_dwordx4 v[108:111], v240, s[24:25] offset:2064
	global_load_dwordx4 v[112:115], v241, s[24:25]
	global_load_dwordx4 v[116:119], v241, s[24:25] offset:16
	global_load_dwordx4 v[120:123], v241, s[24:25] offset:2048
	global_load_dwordx4 v[124:127], v241, s[24:25] offset:2064
	s_mul_i32 s23, s21, 2
	s_add_u32 s23, s20, s23
	s_min_u32 s23, s23, 0x3fff
	s_lshl_b32 s23, s23, 13
	s_add_u32 s24, s12, s23
	s_addc_u32 s25, s13, 0
	global_load_dwordx4 v[128:131], v240, s[24:25]
	global_load_dwordx4 v[132:135], v240, s[24:25] offset:16
	global_load_dwordx4 v[136:139], v240, s[24:25] offset:2048
	global_load_dwordx4 v[140:143], v240, s[24:25] offset:2064
	global_load_dwordx4 v[144:147], v241, s[24:25]
	global_load_dwordx4 v[148:151], v241, s[24:25] offset:16
	global_load_dwordx4 v[152:155], v241, s[24:25] offset:2048
	global_load_dwordx4 v[156:159], v241, s[24:25] offset:2064
	s_mul_i32 s23, s21, 3
	s_add_u32 s23, s20, s23
	s_min_u32 s23, s23, 0x3fff
	s_lshl_b32 s23, s23, 13
	s_add_u32 s24, s12, s23
	s_addc_u32 s25, s13, 0
	global_load_dwordx4 v[176:179], v240, s[24:25]
	global_load_dwordx4 v[180:183], v240, s[24:25] offset:16
	global_load_dwordx4 v[184:187], v240, s[24:25] offset:2048
	global_load_dwordx4 v[188:191], v240, s[24:25] offset:2064
	global_load_dwordx4 v[192:195], v241, s[24:25]
	global_load_dwordx4 v[196:199], v241, s[24:25] offset:16
	global_load_dwordx4 v[200:203], v241, s[24:25] offset:2048
	global_load_dwordx4 v[204:207], v241, s[24:25] offset:2064
	s_waitcnt vmcnt(24)
	v_pk_add_f32 v[236:237], v[64:65], v[66:67]
	v_pk_add_f32 v[236:237], v[236:237], v[68:69]
	v_pk_add_f32 v[236:237], v[236:237], v[70:71]
	v_pk_add_f32 v[236:237], v[236:237], v[72:73]
	v_pk_add_f32 v[236:237], v[236:237], v[74:75]
	v_pk_add_f32 v[236:237], v[236:237], v[76:77]
	v_pk_add_f32 v[236:237], v[236:237], v[78:79]
	v_pk_add_f32 v[236:237], v[236:237], v[80:81]
	v_pk_add_f32 v[236:237], v[236:237], v[82:83]
	v_pk_add_f32 v[236:237], v[236:237], v[84:85]
	v_pk_add_f32 v[236:237], v[236:237], v[86:87]
	v_pk_add_f32 v[236:237], v[236:237], v[88:89]
	v_pk_add_f32 v[236:237], v[236:237], v[90:91]
	v_pk_add_f32 v[236:237], v[236:237], v[92:93]
	v_pk_add_f32 v[236:237], v[236:237], v[94:95]
	v_add_f32_e32 v234, v236, v237
	s_nop 1
	v_add_f32_dpp v234, v234, v234 quad_perm:[1,0,3,2] row_mask:0xf bank_mask:0xf
	s_nop 1
	v_add_f32_dpp v234, v234, v234 quad_perm:[2,3,0,1] row_mask:0xf bank_mask:0xf
	s_nop 1
	v_add_f32_dpp v234, v234, v234 row_half_mirror row_mask:0xf bank_mask:0xf
	s_nop 1
	v_add_f32_dpp v234, v234, v234 row_mirror row_mask:0xf bank_mask:0xf
	s_nop 0
	v_readlane_b32 s26, v234, 0
	v_readlane_b32 s27, v234, 16
	v_readlane_b32 s28, v234, 32
	v_readlane_b32 s29, v234, 48
	v_mov_b32_e32 v234, s26
	v_add_f32_e32 v234, s27, v234
	v_add_f32_e32 v234, s28, v234
	v_add_f32_e32 v234, s29, v234
	v_mul_f32_e32 v216, 0xba000000, v234
	v_pk_add_f32 v[64:65], v[64:65], v[216:217] op_sel_hi:[1,0]
	v_pk_add_f32 v[66:67], v[66:67], v[216:217] op_sel_hi:[1,0]
	v_pk_add_f32 v[68:69], v[68:69], v[216:217] op_sel_hi:[1,0]
; __device__ __forceinline__ void ln_phase(const float* in, float* outf, bf16_t* outb, const float* g, const float* b, int wv0) {
;     ...
;     s = wave_sum(s); const float mu = s * (1.0f / 2048.0f);
;     float sq = 0.f;
; #pragma unroll
;     for (int i = 0; i < 8; ++i) { v[i] -= mu; sq += v[i][0] * v[i][0] + v[i][1] * v[i][1] + v[i][2] * v[i][2] + v[i][3] * v[i][3]; }
;     sq = wave_sum(sq); const float rstd = __builtin_amdgcn_rsqf(sq * (1.0f / 2048.0f) + EPS);
; #pragma unroll
;     for (int i = 0; i < 8; ++i) {
;       const f32x4 y = v[i] * rstd * gg[i] + bb[i];
;       ((f32x4*)(outf + (size_t)row * DM))[i * 64 + lane] = y;
;       if (outb) { u32x2 w; w.x = pk2(y[0], y[1]); w.y = pk2(y[2], y[3]); ((u32x2*)(outb + (size_t)row * DM))[i * 64 + lane] = w; } }
	v_pk_add_f32 v[70:71], v[70:71], v[216:217] op_sel_hi:[1,0]
	v_pk_add_f32 v[72:73], v[72:73], v[216:217] op_sel_hi:[1,0]
	v_pk_add_f32 v[74:75], v[74:75], v[216:217] op_sel_hi:[1,0]
	v_pk_add_f32 v[76:77], v[76:77], v[216:217] op_sel_hi:[1,0]
	v_pk_add_f32 v[78:79], v[78:79], v[216:217] op_sel_hi:[1,0]
	v_pk_add_f32 v[80:81], v[80:81], v[216:217] op_sel_hi:[1,0]
	v_pk_add_f32 v[82:83], v[82:83], v[216:217] op_sel_hi:[1,0]
	v_pk_add_f32 v[84:85], v[84:85], v[216:217] op_sel_hi:[1,0]
	v_pk_add_f32 v[86:87], v[86:87], v[216:217] op_sel_hi:[1,0]
	v_pk_add_f32 v[88:89], v[88:89], v[216:217] op_sel_hi:[1,0]
	v_pk_add_f32 v[90:91], v[90:91], v[216:217] op_sel_hi:[1,0]
	v_pk_add_f32 v[92:93], v[92:93], v[216:217] op_sel_hi:[1,0]
	v_pk_add_f32 v[94:95], v[94:95], v[216:217] op_sel_hi:[1,0]
	v_pk_mul_f32 v[236:237], v[64:65], v[64:65]
	v_pk_fma_f32 v[236:237], v[66:67], v[66:67], v[236:237]
	v_pk_fma_f32 v[236:237], v[68:69], v[68:69], v[236:237]
	v_pk_fma_f32 v[236:237], v[70:71], v[70:71], v[236:237]
	v_pk_fma_f32 v[236:237], v[72:73], v[72:73], v[236:237]
	v_pk_fma_f32 v[236:237], v[74:75], v[74:75], v[236:237]
	v_pk_fma_f32 v[236:237], v[76:77], v[76:77], v[236:237]
	v_pk_fma_f32 v[236:237], v[78:79], v[78:79], v[236:237]
	v_pk_fma_f32 v[236:237], v[80:81], v[80:81], v[236:237]
	v_pk_fma_f32 v[236:237], v[82:83], v[82:83], v[236:237]
	v_pk_fma_f32 v[236:237], v[84:85], v[84:85], v[236:237]
	v_pk_fma_f32 v[236:237], v[86:87], v[86:87], v[236:237]
	v_pk_fma_f32 v[236:237], v[88:89], v[88:89], v[236:237]
	v_pk_fma_f32 v[236:237], v[90:91], v[90:91], v[236:237]
	v_pk_fma_f32 v[236:237], v[92:93], v[92:93], v[236:237]
	v_pk_fma_f32 v[236:237], v[94:95], v[94:95], v[236:237]
	v_add_f32_e32 v235, v236, v237
	s_nop 1
	v_add_f32_dpp v235, v235, v235 quad_perm:[1,0,3,2] row_mask:0xf bank_mask:0xf
	s_nop 1
	v_add_f32_dpp v235, v235, v235 quad_perm:[2,3,0,1] row_mask:0xf bank_mask:0xf
	s_nop 1
	v_add_f32_dpp v235, v235, v235 row_half_mirror row_mask:0xf bank_mask:0xf
	s_nop 1
	v_add_f32_dpp v235, v235, v235 row_mirror row_mask:0xf bank_mask:0xf
	s_nop 0
	v_readlane_b32 s26, v235, 0
	v_readlane_b32 s27, v235, 16
	v_readlane_b32 s28, v235, 32
	v_readlane_b32 s29, v235, 48
	v_mov_b32_e32 v235, s26
	v_add_f32_e32 v235, s27, v235
	v_add_f32_e32 v235, s28, v235
	v_add_f32_e32 v235, s29, v235
	v_fmamk_f32 v235, v235, 0x3a000000, v246
	v_rsq_f32_e32 v217, v235
	s_lshl_b32 s23, s20, 13
	s_lshr_b32 s23, s23, 1
	s_add_u32 s30, s2, s23
	s_addc_u32 s31, s3, 0
	s_lshl_b32 s23, s20, 3
	s_add_u32 s6, s0, s23
	s_addc_u32 s7, s1, 0
	v_mov_b32_e32 v243, 0
	s_mov_b64 exec, 1
	global_store_dwordx2 v243, v[216:217], s[6:7]
	s_mov_b64 exec, -1
	v_pk_mul_f32 v[64:65], v[64:65], v[216:217] op_sel:[0,1] op_sel_hi:[1,1]
	v_pk_mul_f32 v[66:67], v[66:67], v[216:217] op_sel:[0,1] op_sel_hi:[1,1]
	v_pk_fma_f32 v[64:65], v[0:1], v[64:65], v[32:33]
	v_pk_fma_f32 v[66:67], v[2:3], v[66:67], v[34:35]
	v_pk_mul_f32 v[68:69], v[68:69], v[216:217] op_sel:[0,1] op_sel_hi:[1,1]
	v_pk_mul_f32 v[70:71], v[70:71], v[216:217] op_sel:[0,1] op_sel_hi:[1,1]
	v_pk_fma_f32 v[68:69], v[4:5], v[68:69], v[36:37]
	v_pk_fma_f32 v[70:71], v[6:7], v[70:71], v[38:39]
	v_cvt_pk_bf16_f32 v208, v64, v65
	v_cvt_pk_bf16_f32 v209, v66, v67
	v_cvt_pk_bf16_f32 v210, v68, v69
	v_cvt_pk_bf16_f32 v211, v70, v71
	global_store_dwordx4 v242, v[208:211], s[30:31]
	v_pk_mul_f32 v[72:73], v[72:73], v[216:217] op_sel:[0,1] op_sel_hi:[1,1]
	v_pk_mul_f32 v[74:75], v[74:75], v[216:217] op_sel:[0,1] op_sel_hi:[1,1]
	v_pk_fma_f32 v[72:73], v[8:9], v[72:73], v[40:41]
	v_pk_fma_f32 v[74:75], v[10:11], v[74:75], v[42:43]
	v_pk_mul_f32 v[76:77], v[76:77], v[216:217] op_sel:[0,1] op_sel_hi:[1,1]
	v_pk_mul_f32 v[78:79], v[78:79], v[216:217] op_sel:[0,1] op_sel_hi:[1,1]
	v_pk_fma_f32 v[76:77], v[12:13], v[76:77], v[44:45]
	v_pk_fma_f32 v[78:79], v[14:15], v[78:79], v[46:47]
	v_cvt_pk_bf16_f32 v212, v72, v73
	v_cvt_pk_bf16_f32 v213, v74, v75
	v_cvt_pk_bf16_f32 v214, v76, v77
	v_cvt_pk_bf16_f32 v215, v78, v79
	global_store_dwordx4 v242, v[212:215], s[30:31] offset:1024
	v_pk_mul_f32 v[80:81], v[80:81], v[216:217] op_sel:[0,1] op_sel_hi:[1,1]
	v_pk_mul_f32 v[82:83], v[82:83], v[216:217] op_sel:[0,1] op_sel_hi:[1,1]
	v_pk_fma_f32 v[80:81], v[16:17], v[80:81], v[48:49]
	v_pk_fma_f32 v[82:83], v[18:19], v[82:83], v[50:51]
	v_pk_mul_f32 v[84:85], v[84:85], v[216:217] op_sel:[0,1] op_sel_hi:[1,1]
	v_pk_mul_f32 v[86:87], v[86:87], v[216:217] op_sel:[0,1] op_sel_hi:[1,1]
	v_pk_fma_f32 v[84:85], v[20:21], v[84:85], v[52:53]
	v_pk_fma_f32 v[86:87], v[22:23], v[86:87], v[54:55]
	v_cvt_pk_bf16_f32 v208, v80, v81
	v_cvt_pk_bf16_f32 v209, v82, v83
	v_cvt_pk_bf16_f32 v210, v84, v85
	v_cvt_pk_bf16_f32 v211, v86, v87
	global_store_dwordx4 v242, v[208:211], s[30:31] offset:2048
	v_pk_mul_f32 v[88:89], v[88:89], v[216:217] op_sel:[0,1] op_sel_hi:[1,1]
	v_pk_mul_f32 v[90:91], v[90:91], v[216:217] op_sel:[0,1] op_sel_hi:[1,1]
	v_pk_fma_f32 v[88:89], v[24:25], v[88:89], v[56:57]
	v_pk_fma_f32 v[90:91], v[26:27], v[90:91], v[58:59]
	v_pk_mul_f32 v[92:93], v[92:93], v[216:217] op_sel:[0,1] op_sel_hi:[1,1]
	v_pk_mul_f32 v[94:95], v[94:95], v[216:217] op_sel:[0,1] op_sel_hi:[1,1]
	v_pk_fma_f32 v[92:93], v[28:29], v[92:93], v[60:61]
	v_pk_fma_f32 v[94:95], v[30:31], v[94:95], v[62:63]
	v_cvt_pk_bf16_f32 v212, v88, v89
	v_cvt_pk_bf16_f32 v213, v90, v91
	v_cvt_pk_bf16_f32 v214, v92, v93
	v_cvt_pk_bf16_f32 v215, v94, v95
	global_store_dwordx4 v242, v[212:215], s[30:31] offset:3072
	s_add_u32 s20, s20, s21
	s_cmp_ge_u32 s20, 0x4000
	s_cbranch_scc1 .Lln2a_done
; __device__ __forceinline__ void ln_phase(const float* in, float* outf, bf16_t* outb, const float* g, const float* b, int wv0) {
;     ...
;   for (int row = wv; row < NTOK; row += nwv) {
;     f32x4 v[8]; float s = 0.f;
; #pragma unroll
;     for (int i = 0; i < 8; ++i) v[i] = vn[i];
;     if (row + nwv < NTOK) { const f32x4* ir = (const f32x4*)(in + (size_t)(row + nwv) * DM);
; #pragma unroll
;       for (int i = 0; i < 8; ++i) vn[i] = ir[i * 64 + lane]; }
; #pragma unroll
;     for (int i = 0; i < 8; ++i) s += v[i][0] + v[i][1] + v[i][2] + v[i][3];
;     s = wave_sum(s); const float mu = s * (1.0f / 2048.0f);
;     float sq = 0.f;
; #pragma unroll
;     for (int i = 0; i < 8; ++i) { v[i] -= mu; sq += v[i][0] * v[i][0] + v[i][1] * v[i][1] + v[i][2] * v[i][2] + v[i][3] * v[i][3]; }
;     sq = wave_sum(sq); const float rstd = __builtin_amdgcn_rsqf(sq * (1.0f / 2048.0f) + EPS);
; #pragma unroll
;     for (int i = 0; i < 8; ++i) {
;       const f32x4 y = v[i] * rstd * gg[i] + bb[i];
	s_mul_i32 s23, s21, 3
	s_add_u32 s23, s20, s23
	s_min_u32 s23, s23, 0x3fff
	s_lshl_b32 s23, s23, 13
	s_add_u32 s24, s12, s23
	s_addc_u32 s25, s13, 0
	global_load_dwordx4 v[64:67], v240, s[24:25]
	global_load_dwordx4 v[68:71], v240, s[24:25] offset:16
	global_load_dwordx4 v[72:75], v240, s[24:25] offset:2048
	global_load_dwordx4 v[76:79], v240, s[24:25] offset:2064
	global_load_dwordx4 v[80:83], v241, s[24:25]
	global_load_dwordx4 v[84:87], v241, s[24:25] offset:16
	global_load_dwordx4 v[88:91], v241, s[24:25] offset:2048
	global_load_dwordx4 v[92:95], v241, s[24:25] offset:2064
	s_waitcnt vmcnt(29)
	v_pk_add_f32 v[236:237], v[96:97], v[98:99]
	v_pk_add_f32 v[236:237], v[236:237], v[100:101]
	v_pk_add_f32 v[236:237], v[236:237], v[102:103]
	v_pk_add_f32 v[236:237], v[236:237], v[104:105]
	v_pk_add_f32 v[236:237], v[236:237], v[106:107]
	v_pk_add_f32 v[236:237], v[236:237], v[108:109]
	v_pk_add_f32 v[236:237], v[236:237], v[110:111]
	v_pk_add_f32 v[236:237], v[236:237], v[112:113]
	v_pk_add_f32 v[236:237], v[236:237], v[114:115]
	v_pk_add_f32 v[236:237], v[236:237], v[116:117]
	v_pk_add_f32 v[236:237], v[236:237], v[118:119]
	v_pk_add_f32 v[236:237], v[236:237], v[120:121]
	v_pk_add_f32 v[236:237], v[236:237], v[122:123]
	v_pk_add_f32 v[236:237], v[236:237], v[124:125]
	v_pk_add_f32 v[236:237], v[236:237], v[126:127]
	v_add_f32_e32 v234, v236, v237
	s_nop 1
	v_add_f32_dpp v234, v234, v234 quad_perm:[1,0,3,2] row_mask:0xf bank_mask:0xf
	s_nop 1
	v_add_f32_dpp v234, v234, v234 quad_perm:[2,3,0,1] row_mask:0xf bank_mask:0xf
	s_nop 1
	v_add_f32_dpp v234, v234, v234 row_half_mirror row_mask:0xf bank_mask:0xf
	s_nop 1
	v_add_f32_dpp v234, v234, v234 row_mirror row_mask:0xf bank_mask:0xf
	s_nop 0
	v_readlane_b32 s26, v234, 0
	v_readlane_b32 s27, v234, 16
	v_readlane_b32 s28, v234, 32
	v_readlane_b32 s29, v234, 48
	v_mov_b32_e32 v234, s26
	v_add_f32_e32 v234, s27, v234
	v_add_f32_e32 v234, s28, v234
	v_add_f32_e32 v234, s29, v234
	v_mul_f32_e32 v216, 0xba000000, v234
	v_pk_add_f32 v[96:97], v[96:97], v[216:217] op_sel_hi:[1,0]
	v_pk_add_f32 v[98:99], v[98:99], v[216:217] op_sel_hi:[1,0]
	v_pk_add_f32 v[100:101], v[100:101], v[216:217] op_sel_hi:[1,0]
	v_pk_add_f32 v[102:103], v[102:103], v[216:217] op_sel_hi:[1,0]
	v_pk_add_f32 v[104:105], v[104:105], v[216:217] op_sel_hi:[1,0]
	v_pk_add_f32 v[106:107], v[106:107], v[216:217] op_sel_hi:[1,0]
	v_pk_add_f32 v[108:109], v[108:109], v[216:217] op_sel_hi:[1,0]
	v_pk_add_f32 v[110:111], v[110:111], v[216:217] op_sel_hi:[1,0]
	v_pk_add_f32 v[112:113], v[112:113], v[216:217] op_sel_hi:[1,0]
	v_pk_add_f32 v[114:115], v[114:115], v[216:217] op_sel_hi:[1,0]
	v_pk_add_f32 v[116:117], v[116:117], v[216:217] op_sel_hi:[1,0]
	v_pk_add_f32 v[118:119], v[118:119], v[216:217] op_sel_hi:[1,0]
	v_pk_add_f32 v[120:121], v[120:121], v[216:217] op_sel_hi:[1,0]
	v_pk_add_f32 v[122:123], v[122:123], v[216:217] op_sel_hi:[1,0]
	v_pk_add_f32 v[124:125], v[124:125], v[216:217] op_sel_hi:[1,0]
	v_pk_add_f32 v[126:127], v[126:127], v[216:217] op_sel_hi:[1,0]
	v_pk_mul_f32 v[236:237], v[96:97], v[96:97]
	v_pk_fma_f32 v[236:237], v[98:99], v[98:99], v[236:237]
	v_pk_fma_f32 v[236:237], v[100:101], v[100:101], v[236:237]
	v_pk_fma_f32 v[236:237], v[102:103], v[102:103], v[236:237]
	v_pk_fma_f32 v[236:237], v[104:105], v[104:105], v[236:237]
	v_pk_fma_f32 v[236:237], v[106:107], v[106:107], v[236:237]
	v_pk_fma_f32 v[236:237], v[108:109], v[108:109], v[236:237]
	v_pk_fma_f32 v[236:237], v[110:111], v[110:111], v[236:237]
	v_pk_fma_f32 v[236:237], v[112:113], v[112:113], v[236:237]
	v_pk_fma_f32 v[236:237], v[114:115], v[114:115], v[236:237]
	v_pk_fma_f32 v[236:237], v[116:117], v[116:117], v[236:237]
	v_pk_fma_f32 v[236:237], v[118:119], v[118:119], v[236:237]
	v_pk_fma_f32 v[236:237], v[120:121], v[120:121], v[236:237]
	v_pk_fma_f32 v[236:237], v[122:123], v[122:123], v[236:237]
	v_pk_fma_f32 v[236:237], v[124:125], v[124:125], v[236:237]
	v_pk_fma_f32 v[236:237], v[126:127], v[126:127], v[236:237]
	v_add_f32_e32 v235, v236, v237
	s_nop 1
	v_add_f32_dpp v235, v235, v235 quad_perm:[1,0,3,2] row_mask:0xf bank_mask:0xf
	s_nop 1
	v_add_f32_dpp v235, v235, v235 quad_perm:[2,3,0,1] row_mask:0xf bank_mask:0xf
	s_nop 1
	v_add_f32_dpp v235, v235, v235 row_half_mirror row_mask:0xf bank_mask:0xf
	s_nop 1
	v_add_f32_dpp v235, v235, v235 row_mirror row_mask:0xf bank_mask:0xf
	s_nop 0
	v_readlane_b32 s26, v235, 0
	v_readlane_b32 s27, v235, 16
	v_readlane_b32 s28, v235, 32
	v_readlane_b32 s29, v235, 48
	v_mov_b32_e32 v235, s26
	v_add_f32_e32 v235, s27, v235
	v_add_f32_e32 v235, s28, v235
	v_add_f32_e32 v235, s29, v235
	v_fmamk_f32 v235, v235, 0x3a000000, v246
	v_rsq_f32_e32 v217, v235
	s_lshl_b32 s23, s20, 13
	s_lshr_b32 s23, s23, 1
	s_add_u32 s30, s2, s23
	s_addc_u32 s31, s3, 0
	s_lshl_b32 s23, s20, 3
	s_add_u32 s6, s0, s23
	s_addc_u32 s7, s1, 0
	v_mov_b32_e32 v243, 0
	s_mov_b64 exec, 1
	global_store_dwordx2 v243, v[216:217], s[6:7]
	s_mov_b64 exec, -1
	v_pk_mul_f32 v[96:97], v[96:97], v[216:217] op_sel:[0,1] op_sel_hi:[1,1]
	v_pk_mul_f32 v[98:99], v[98:99], v[216:217] op_sel:[0,1] op_sel_hi:[1,1]
	v_pk_fma_f32 v[96:97], v[0:1], v[96:97], v[32:33]
	v_pk_fma_f32 v[98:99], v[2:3], v[98:99], v[34:35]
	v_pk_mul_f32 v[100:101], v[100:101], v[216:217] op_sel:[0,1] op_sel_hi:[1,1]
	v_pk_mul_f32 v[102:103], v[102:103], v[216:217] op_sel:[0,1] op_sel_hi:[1,1]
	v_pk_fma_f32 v[100:101], v[4:5], v[100:101], v[36:37]
	v_pk_fma_f32 v[102:103], v[6:7], v[102:103], v[38:39]
	v_cvt_pk_bf16_f32 v208, v96, v97
	v_cvt_pk_bf16_f32 v209, v98, v99
	v_cvt_pk_bf16_f32 v210, v100, v101
	v_cvt_pk_bf16_f32 v211, v102, v103
	global_store_dwordx4 v242, v[208:211], s[30:31]
; __device__ __forceinline__ void ln_phase(const float* in, float* outf, bf16_t* outb, const float* g, const float* b, int wv0) {
;     ...
;   for (int row = wv; row < NTOK; row += nwv) {
;     f32x4 v[8]; float s = 0.f;
; #pragma unroll
;     for (int i = 0; i < 8; ++i) v[i] = vn[i];
;     if (row + nwv < NTOK) { const f32x4* ir = (const f32x4*)(in + (size_t)(row + nwv) * DM);
; #pragma unroll
;       for (int i = 0; i < 8; ++i) vn[i] = ir[i * 64 + lane]; }
; #pragma unroll
;     for (int i = 0; i < 8; ++i) s += v[i][0] + v[i][1] + v[i][2] + v[i][3];
;     s = wave_sum(s); const float mu = s * (1.0f / 2048.0f);
;     float sq = 0.f;
; #pragma unroll
;     for (int i = 0; i < 8; ++i) { v[i] -= mu; sq += v[i][0] * v[i][0] + v[i][1] * v[i][1] + v[i][2] * v[i][2] + v[i][3] * v[i][3]; }
;     sq = wave_sum(sq); const float rstd = __builtin_amdgcn_rsqf(sq * (1.0f / 2048.0f) + EPS);
; #pragma unroll
;     for (int i = 0; i < 8; ++i) {
;       const f32x4 y = v[i] * rstd * gg[i] + bb[i];
	v_pk_mul_f32 v[104:105], v[104:105], v[216:217] op_sel:[0,1] op_sel_hi:[1,1]
	v_pk_mul_f32 v[106:107], v[106:107], v[216:217] op_sel:[0,1] op_sel_hi:[1,1]
	v_pk_fma_f32 v[104:105], v[8:9], v[104:105], v[40:41]
	v_pk_fma_f32 v[106:107], v[10:11], v[106:107], v[42:43]
	v_pk_mul_f32 v[108:109], v[108:109], v[216:217] op_sel:[0,1] op_sel_hi:[1,1]
	v_pk_mul_f32 v[110:111], v[110:111], v[216:217] op_sel:[0,1] op_sel_hi:[1,1]
	v_pk_fma_f32 v[108:109], v[12:13], v[108:109], v[44:45]
	v_pk_fma_f32 v[110:111], v[14:15], v[110:111], v[46:47]
	v_cvt_pk_bf16_f32 v212, v104, v105
	v_cvt_pk_bf16_f32 v213, v106, v107
	v_cvt_pk_bf16_f32 v214, v108, v109
	v_cvt_pk_bf16_f32 v215, v110, v111
	global_store_dwordx4 v242, v[212:215], s[30:31] offset:1024
	v_pk_mul_f32 v[112:113], v[112:113], v[216:217] op_sel:[0,1] op_sel_hi:[1,1]
	v_pk_mul_f32 v[114:115], v[114:115], v[216:217] op_sel:[0,1] op_sel_hi:[1,1]
	v_pk_fma_f32 v[112:113], v[16:17], v[112:113], v[48:49]
	v_pk_fma_f32 v[114:115], v[18:19], v[114:115], v[50:51]
	v_pk_mul_f32 v[116:117], v[116:117], v[216:217] op_sel:[0,1] op_sel_hi:[1,1]
	v_pk_mul_f32 v[118:119], v[118:119], v[216:217] op_sel:[0,1] op_sel_hi:[1,1]
	v_pk_fma_f32 v[116:117], v[20:21], v[116:117], v[52:53]
	v_pk_fma_f32 v[118:119], v[22:23], v[118:119], v[54:55]
	v_cvt_pk_bf16_f32 v208, v112, v113
	v_cvt_pk_bf16_f32 v209, v114, v115
	v_cvt_pk_bf16_f32 v210, v116, v117
	v_cvt_pk_bf16_f32 v211, v118, v119
	global_store_dwordx4 v242, v[208:211], s[30:31] offset:2048
	v_pk_mul_f32 v[120:121], v[120:121], v[216:217] op_sel:[0,1] op_sel_hi:[1,1]
	v_pk_mul_f32 v[122:123], v[122:123], v[216:217] op_sel:[0,1] op_sel_hi:[1,1]
	v_pk_fma_f32 v[120:121], v[24:25], v[120:121], v[56:57]
	v_pk_fma_f32 v[122:123], v[26:27], v[122:123], v[58:59]
	v_pk_mul_f32 v[124:125], v[124:125], v[216:217] op_sel:[0,1] op_sel_hi:[1,1]
	v_pk_mul_f32 v[126:127], v[126:127], v[216:217] op_sel:[0,1] op_sel_hi:[1,1]
	v_pk_fma_f32 v[124:125], v[28:29], v[124:125], v[60:61]
	v_pk_fma_f32 v[126:127], v[30:31], v[126:127], v[62:63]
	v_cvt_pk_bf16_f32 v212, v120, v121
	v_cvt_pk_bf16_f32 v213, v122, v123
	v_cvt_pk_bf16_f32 v214, v124, v125
	v_cvt_pk_bf16_f32 v215, v126, v127
	global_store_dwordx4 v242, v[212:215], s[30:31] offset:3072
	s_add_u32 s20, s20, s21
	s_cmp_ge_u32 s20, 0x4000
	s_cbranch_scc1 .Lln2a_done
	s_mul_i32 s23, s21, 3
	s_add_u32 s23, s20, s23
	s_min_u32 s23, s23, 0x3fff
	s_lshl_b32 s23, s23, 13
	s_add_u32 s24, s12, s23
	s_addc_u32 s25, s13, 0
	global_load_dwordx4 v[96:99], v240, s[24:25]
	global_load_dwordx4 v[100:103], v240, s[24:25] offset:16
	global_load_dwordx4 v[104:107], v240, s[24:25] offset:2048
	global_load_dwordx4 v[108:111], v240, s[24:25] offset:2064
	global_load_dwordx4 v[112:115], v241, s[24:25]
	global_load_dwordx4 v[116:119], v241, s[24:25] offset:16
	global_load_dwordx4 v[120:123], v241, s[24:25] offset:2048
	global_load_dwordx4 v[124:127], v241, s[24:25] offset:2064
	s_waitcnt vmcnt(34)
	v_pk_add_f32 v[236:237], v[128:129], v[130:131]
	v_pk_add_f32 v[236:237], v[236:237], v[132:133]
	v_pk_add_f32 v[236:237], v[236:237], v[134:135]
	v_pk_add_f32 v[236:237], v[236:237], v[136:137]
	v_pk_add_f32 v[236:237], v[236:237], v[138:139]
	v_pk_add_f32 v[236:237], v[236:237], v[140:141]
	v_pk_add_f32 v[236:237], v[236:237], v[142:143]
	v_pk_add_f32 v[236:237], v[236:237], v[144:145]
	v_pk_add_f32 v[236:237], v[236:237], v[146:147]
	v_pk_add_f32 v[236:237], v[236:237], v[148:149]
	v_pk_add_f32 v[236:237], v[236:237], v[150:151]
	v_pk_add_f32 v[236:237], v[236:237], v[152:153]
	v_pk_add_f32 v[236:237], v[236:237], v[154:155]
	v_pk_add_f32 v[236:237], v[236:237], v[156:157]
	v_pk_add_f32 v[236:237], v[236:237], v[158:159]
	v_add_f32_e32 v234, v236, v237
	s_nop 1
	v_add_f32_dpp v234, v234, v234 quad_perm:[1,0,3,2] row_mask:0xf bank_mask:0xf
	s_nop 1
	v_add_f32_dpp v234, v234, v234 quad_perm:[2,3,0,1] row_mask:0xf bank_mask:0xf
	s_nop 1
	v_add_f32_dpp v234, v234, v234 row_half_mirror row_mask:0xf bank_mask:0xf
	s_nop 1
	v_add_f32_dpp v234, v234, v234 row_mirror row_mask:0xf bank_mask:0xf
	s_nop 0
	v_readlane_b32 s26, v234, 0
	v_readlane_b32 s27, v234, 16
	v_readlane_b32 s28, v234, 32
	v_readlane_b32 s29, v234, 48
	v_mov_b32_e32 v234, s26
	v_add_f32_e32 v234, s27, v234
	v_add_f32_e32 v234, s28, v234
	v_add_f32_e32 v234, s29, v234
	v_mul_f32_e32 v216, 0xba000000, v234
	v_pk_add_f32 v[128:129], v[128:129], v[216:217] op_sel_hi:[1,0]
	v_pk_add_f32 v[130:131], v[130:131], v[216:217] op_sel_hi:[1,0]
	v_pk_add_f32 v[132:133], v[132:133], v[216:217] op_sel_hi:[1,0]
	v_pk_add_f32 v[134:135], v[134:135], v[216:217] op_sel_hi:[1,0]
	v_pk_add_f32 v[136:137], v[136:137], v[216:217] op_sel_hi:[1,0]
	v_pk_add_f32 v[138:139], v[138:139], v[216:217] op_sel_hi:[1,0]
	v_pk_add_f32 v[140:141], v[140:141], v[216:217] op_sel_hi:[1,0]
	v_pk_add_f32 v[142:143], v[142:143], v[216:217] op_sel_hi:[1,0]
	v_pk_add_f32 v[144:145], v[144:145], v[216:217] op_sel_hi:[1,0]
	v_pk_add_f32 v[146:147], v[146:147], v[216:217] op_sel_hi:[1,0]
	v_pk_add_f32 v[148:149], v[148:149], v[216:217] op_sel_hi:[1,0]
	v_pk_add_f32 v[150:151], v[150:151], v[216:217] op_sel_hi:[1,0]
	v_pk_add_f32 v[152:153], v[152:153], v[216:217] op_sel_hi:[1,0]
	v_pk_add_f32 v[154:155], v[154:155], v[216:217] op_sel_hi:[1,0]
	v_pk_add_f32 v[156:157], v[156:157], v[216:217] op_sel_hi:[1,0]
	v_pk_add_f32 v[158:159], v[158:159], v[216:217] op_sel_hi:[1,0]
	v_pk_mul_f32 v[236:237], v[128:129], v[128:129]
	v_pk_fma_f32 v[236:237], v[130:131], v[130:131], v[236:237]
	v_pk_fma_f32 v[236:237], v[132:133], v[132:133], v[236:237]
	v_pk_fma_f32 v[236:237], v[134:135], v[134:135], v[236:237]
	v_pk_fma_f32 v[236:237], v[136:137], v[136:137], v[236:237]
; __device__ __forceinline__ void ln_phase(const float* in, float* outf, bf16_t* outb, const float* g, const float* b, int wv0) {
;     ...
;     for (int i = 0; i < 8; ++i) { v[i] -= mu; sq += v[i][0] * v[i][0] + v[i][1] * v[i][1] + v[i][2] * v[i][2] + v[i][3] * v[i][3]; }
;     sq = wave_sum(sq); const float rstd = __builtin_amdgcn_rsqf(sq * (1.0f / 2048.0f) + EPS);
; #pragma unroll
;     for (int i = 0; i < 8; ++i) {
;       const f32x4 y = v[i] * rstd * gg[i] + bb[i];
;       ((f32x4*)(outf + (size_t)row * DM))[i * 64 + lane] = y;
;       if (outb) { u32x2 w; w.x = pk2(y[0], y[1]); w.y = pk2(y[2], y[3]); ((u32x2*)(outb + (size_t)row * DM))[i * 64 + lane] = w; } }
	v_pk_fma_f32 v[236:237], v[138:139], v[138:139], v[236:237]
	v_pk_fma_f32 v[236:237], v[140:141], v[140:141], v[236:237]
	v_pk_fma_f32 v[236:237], v[142:143], v[142:143], v[236:237]
	v_pk_fma_f32 v[236:237], v[144:145], v[144:145], v[236:237]
	v_pk_fma_f32 v[236:237], v[146:147], v[146:147], v[236:237]
	v_pk_fma_f32 v[236:237], v[148:149], v[148:149], v[236:237]
	v_pk_fma_f32 v[236:237], v[150:151], v[150:151], v[236:237]
	v_pk_fma_f32 v[236:237], v[152:153], v[152:153], v[236:237]
	v_pk_fma_f32 v[236:237], v[154:155], v[154:155], v[236:237]
	v_pk_fma_f32 v[236:237], v[156:157], v[156:157], v[236:237]
	v_pk_fma_f32 v[236:237], v[158:159], v[158:159], v[236:237]
	v_add_f32_e32 v235, v236, v237
	s_nop 1
	v_add_f32_dpp v235, v235, v235 quad_perm:[1,0,3,2] row_mask:0xf bank_mask:0xf
	s_nop 1
	v_add_f32_dpp v235, v235, v235 quad_perm:[2,3,0,1] row_mask:0xf bank_mask:0xf
	s_nop 1
	v_add_f32_dpp v235, v235, v235 row_half_mirror row_mask:0xf bank_mask:0xf
	s_nop 1
	v_add_f32_dpp v235, v235, v235 row_mirror row_mask:0xf bank_mask:0xf
	s_nop 0
	v_readlane_b32 s26, v235, 0
	v_readlane_b32 s27, v235, 16
	v_readlane_b32 s28, v235, 32
	v_readlane_b32 s29, v235, 48
	v_mov_b32_e32 v235, s26
	v_add_f32_e32 v235, s27, v235
	v_add_f32_e32 v235, s28, v235
	v_add_f32_e32 v235, s29, v235
	v_fmamk_f32 v235, v235, 0x3a000000, v246
	v_rsq_f32_e32 v217, v235
	s_lshl_b32 s23, s20, 13
	s_lshr_b32 s23, s23, 1
	s_add_u32 s30, s2, s23
	s_addc_u32 s31, s3, 0
	s_lshl_b32 s23, s20, 3
	s_add_u32 s6, s0, s23
	s_addc_u32 s7, s1, 0
	v_mov_b32_e32 v243, 0
	s_mov_b64 exec, 1
	global_store_dwordx2 v243, v[216:217], s[6:7]
	s_mov_b64 exec, -1
	v_pk_mul_f32 v[128:129], v[128:129], v[216:217] op_sel:[0,1] op_sel_hi:[1,1]
	v_pk_mul_f32 v[130:131], v[130:131], v[216:217] op_sel:[0,1] op_sel_hi:[1,1]
	v_pk_fma_f32 v[128:129], v[0:1], v[128:129], v[32:33]
	v_pk_fma_f32 v[130:131], v[2:3], v[130:131], v[34:35]
	v_pk_mul_f32 v[132:133], v[132:133], v[216:217] op_sel:[0,1] op_sel_hi:[1,1]
	v_pk_mul_f32 v[134:135], v[134:135], v[216:217] op_sel:[0,1] op_sel_hi:[1,1]
	v_pk_fma_f32 v[132:133], v[4:5], v[132:133], v[36:37]
	v_pk_fma_f32 v[134:135], v[6:7], v[134:135], v[38:39]
	v_cvt_pk_bf16_f32 v208, v128, v129
	v_cvt_pk_bf16_f32 v209, v130, v131
	v_cvt_pk_bf16_f32 v210, v132, v133
	v_cvt_pk_bf16_f32 v211, v134, v135
	global_store_dwordx4 v242, v[208:211], s[30:31]
	v_pk_mul_f32 v[136:137], v[136:137], v[216:217] op_sel:[0,1] op_sel_hi:[1,1]
	v_pk_mul_f32 v[138:139], v[138:139], v[216:217] op_sel:[0,1] op_sel_hi:[1,1]
	v_pk_fma_f32 v[136:137], v[8:9], v[136:137], v[40:41]
	v_pk_fma_f32 v[138:139], v[10:11], v[138:139], v[42:43]
	v_pk_mul_f32 v[140:141], v[140:141], v[216:217] op_sel:[0,1] op_sel_hi:[1,1]
	v_pk_mul_f32 v[142:143], v[142:143], v[216:217] op_sel:[0,1] op_sel_hi:[1,1]
	v_pk_fma_f32 v[140:141], v[12:13], v[140:141], v[44:45]
	v_pk_fma_f32 v[142:143], v[14:15], v[142:143], v[46:47]
	v_cvt_pk_bf16_f32 v212, v136, v137
	v_cvt_pk_bf16_f32 v213, v138, v139
	v_cvt_pk_bf16_f32 v214, v140, v141
	v_cvt_pk_bf16_f32 v215, v142, v143
	global_store_dwordx4 v242, v[212:215], s[30:31] offset:1024
	v_pk_mul_f32 v[144:145], v[144:145], v[216:217] op_sel:[0,1] op_sel_hi:[1,1]
	v_pk_mul_f32 v[146:147], v[146:147], v[216:217] op_sel:[0,1] op_sel_hi:[1,1]
	v_pk_fma_f32 v[144:145], v[16:17], v[144:145], v[48:49]
	v_pk_fma_f32 v[146:147], v[18:19], v[146:147], v[50:51]
	v_pk_mul_f32 v[148:149], v[148:149], v[216:217] op_sel:[0,1] op_sel_hi:[1,1]
	v_pk_mul_f32 v[150:151], v[150:151], v[216:217] op_sel:[0,1] op_sel_hi:[1,1]
	v_pk_fma_f32 v[148:149], v[20:21], v[148:149], v[52:53]
	v_pk_fma_f32 v[150:151], v[22:23], v[150:151], v[54:55]
	v_cvt_pk_bf16_f32 v208, v144, v145
	v_cvt_pk_bf16_f32 v209, v146, v147
	v_cvt_pk_bf16_f32 v210, v148, v149
	v_cvt_pk_bf16_f32 v211, v150, v151
	global_store_dwordx4 v242, v[208:211], s[30:31] offset:2048
	v_pk_mul_f32 v[152:153], v[152:153], v[216:217] op_sel:[0,1] op_sel_hi:[1,1]
	v_pk_mul_f32 v[154:155], v[154:155], v[216:217] op_sel:[0,1] op_sel_hi:[1,1]
	v_pk_fma_f32 v[152:153], v[24:25], v[152:153], v[56:57]
	v_pk_fma_f32 v[154:155], v[26:27], v[154:155], v[58:59]
	v_pk_mul_f32 v[156:157], v[156:157], v[216:217] op_sel:[0,1] op_sel_hi:[1,1]
	v_pk_mul_f32 v[158:159], v[158:159], v[216:217] op_sel:[0,1] op_sel_hi:[1,1]
	v_pk_fma_f32 v[156:157], v[28:29], v[156:157], v[60:61]
	v_pk_fma_f32 v[158:159], v[30:31], v[158:159], v[62:63]
	v_cvt_pk_bf16_f32 v212, v152, v153
	v_cvt_pk_bf16_f32 v213, v154, v155
	v_cvt_pk_bf16_f32 v214, v156, v157
	v_cvt_pk_bf16_f32 v215, v158, v159
	global_store_dwordx4 v242, v[212:215], s[30:31] offset:3072
	s_add_u32 s20, s20, s21
	s_cmp_ge_u32 s20, 0x4000
	s_cbranch_scc1 .Lln2a_done
; __device__ __forceinline__ void ln_phase(const float* in, float* outf, bf16_t* outb, const float* g, const float* b, int wv0) {
;     ...
;   for (int row = wv; row < NTOK; row += nwv) {
;     f32x4 v[8]; float s = 0.f;
; #pragma unroll
;     for (int i = 0; i < 8; ++i) v[i] = vn[i];
;     if (row + nwv < NTOK) { const f32x4* ir = (const f32x4*)(in + (size_t)(row + nwv) * DM);
; #pragma unroll
;       for (int i = 0; i < 8; ++i) vn[i] = ir[i * 64 + lane]; }
; #pragma unroll
;     for (int i = 0; i < 8; ++i) s += v[i][0] + v[i][1] + v[i][2] + v[i][3];
;     s = wave_sum(s); const float mu = s * (1.0f / 2048.0f);
;     float sq = 0.f;
; #pragma unroll
;     for (int i = 0; i < 8; ++i) { v[i] -= mu; sq += v[i][0] * v[i][0] + v[i][1] * v[i][1] + v[i][2] * v[i][2] + v[i][3] * v[i][3]; }
;     sq = wave_sum(sq); const float rstd = __builtin_amdgcn_rsqf(sq * (1.0f / 2048.0f) + EPS);
; #pragma unroll
;     for (int i = 0; i < 8; ++i) {
;       const f32x4 y = v[i] * rstd * gg[i] + bb[i];
.Lln2a_loop:
	s_mul_i32 s23, s21, 3
	s_add_u32 s23, s20, s23
	s_min_u32 s23, s23, 0x3fff
	s_lshl_b32 s23, s23, 13
	s_add_u32 s24, s12, s23
	s_addc_u32 s25, s13, 0
	global_load_dwordx4 v[128:131], v240, s[24:25]
	global_load_dwordx4 v[132:135], v240, s[24:25] offset:16
	global_load_dwordx4 v[136:139], v240, s[24:25] offset:2048
	global_load_dwordx4 v[140:143], v240, s[24:25] offset:2064
	global_load_dwordx4 v[144:147], v241, s[24:25]
	global_load_dwordx4 v[148:151], v241, s[24:25] offset:16
	global_load_dwordx4 v[152:155], v241, s[24:25] offset:2048
	global_load_dwordx4 v[156:159], v241, s[24:25] offset:2064
	s_waitcnt vmcnt(39)
	v_pk_add_f32 v[236:237], v[176:177], v[178:179]
	v_pk_add_f32 v[236:237], v[236:237], v[180:181]
	v_pk_add_f32 v[236:237], v[236:237], v[182:183]
	v_pk_add_f32 v[236:237], v[236:237], v[184:185]
	v_pk_add_f32 v[236:237], v[236:237], v[186:187]
	v_pk_add_f32 v[236:237], v[236:237], v[188:189]
	v_pk_add_f32 v[236:237], v[236:237], v[190:191]
	v_pk_add_f32 v[236:237], v[236:237], v[192:193]
	v_pk_add_f32 v[236:237], v[236:237], v[194:195]
	v_pk_add_f32 v[236:237], v[236:237], v[196:197]
	v_pk_add_f32 v[236:237], v[236:237], v[198:199]
	v_pk_add_f32 v[236:237], v[236:237], v[200:201]
	v_pk_add_f32 v[236:237], v[236:237], v[202:203]
	v_pk_add_f32 v[236:237], v[236:237], v[204:205]
	v_pk_add_f32 v[236:237], v[236:237], v[206:207]
	v_add_f32_e32 v234, v236, v237
	s_nop 1
	v_add_f32_dpp v234, v234, v234 quad_perm:[1,0,3,2] row_mask:0xf bank_mask:0xf
	s_nop 1
	v_add_f32_dpp v234, v234, v234 quad_perm:[2,3,0,1] row_mask:0xf bank_mask:0xf
	s_nop 1
	v_add_f32_dpp v234, v234, v234 row_half_mirror row_mask:0xf bank_mask:0xf
	s_nop 1
	v_add_f32_dpp v234, v234, v234 row_mirror row_mask:0xf bank_mask:0xf
	s_nop 0
	v_readlane_b32 s26, v234, 0
	v_readlane_b32 s27, v234, 16
	v_readlane_b32 s28, v234, 32
	v_readlane_b32 s29, v234, 48
	v_mov_b32_e32 v234, s26
	v_add_f32_e32 v234, s27, v234
	v_add_f32_e32 v234, s28, v234
	v_add_f32_e32 v234, s29, v234
	v_mul_f32_e32 v216, 0xba000000, v234
	v_pk_add_f32 v[176:177], v[176:177], v[216:217] op_sel_hi:[1,0]
	v_pk_add_f32 v[178:179], v[178:179], v[216:217] op_sel_hi:[1,0]
	v_pk_add_f32 v[180:181], v[180:181], v[216:217] op_sel_hi:[1,0]
	v_pk_add_f32 v[182:183], v[182:183], v[216:217] op_sel_hi:[1,0]
	v_pk_add_f32 v[184:185], v[184:185], v[216:217] op_sel_hi:[1,0]
	v_pk_add_f32 v[186:187], v[186:187], v[216:217] op_sel_hi:[1,0]
	v_pk_add_f32 v[188:189], v[188:189], v[216:217] op_sel_hi:[1,0]
	v_pk_add_f32 v[190:191], v[190:191], v[216:217] op_sel_hi:[1,0]
	v_pk_add_f32 v[192:193], v[192:193], v[216:217] op_sel_hi:[1,0]
	v_pk_add_f32 v[194:195], v[194:195], v[216:217] op_sel_hi:[1,0]
	v_pk_add_f32 v[196:197], v[196:197], v[216:217] op_sel_hi:[1,0]
	v_pk_add_f32 v[198:199], v[198:199], v[216:217] op_sel_hi:[1,0]
	v_pk_add_f32 v[200:201], v[200:201], v[216:217] op_sel_hi:[1,0]
	v_pk_add_f32 v[202:203], v[202:203], v[216:217] op_sel_hi:[1,0]
	v_pk_add_f32 v[204:205], v[204:205], v[216:217] op_sel_hi:[1,0]
	v_pk_add_f32 v[206:207], v[206:207], v[216:217] op_sel_hi:[1,0]
	v_pk_mul_f32 v[236:237], v[176:177], v[176:177]
	v_pk_fma_f32 v[236:237], v[178:179], v[178:179], v[236:237]
	v_pk_fma_f32 v[236:237], v[180:181], v[180:181], v[236:237]
	v_pk_fma_f32 v[236:237], v[182:183], v[182:183], v[236:237]
	v_pk_fma_f32 v[236:237], v[184:185], v[184:185], v[236:237]
	v_pk_fma_f32 v[236:237], v[186:187], v[186:187], v[236:237]
	v_pk_fma_f32 v[236:237], v[188:189], v[188:189], v[236:237]
	v_pk_fma_f32 v[236:237], v[190:191], v[190:191], v[236:237]
	v_pk_fma_f32 v[236:237], v[192:193], v[192:193], v[236:237]
	v_pk_fma_f32 v[236:237], v[194:195], v[194:195], v[236:237]
	v_pk_fma_f32 v[236:237], v[196:197], v[196:197], v[236:237]
	v_pk_fma_f32 v[236:237], v[198:199], v[198:199], v[236:237]
	v_pk_fma_f32 v[236:237], v[200:201], v[200:201], v[236:237]
	v_pk_fma_f32 v[236:237], v[202:203], v[202:203], v[236:237]
	v_pk_fma_f32 v[236:237], v[204:205], v[204:205], v[236:237]
	v_pk_fma_f32 v[236:237], v[206:207], v[206:207], v[236:237]
	v_add_f32_e32 v235, v236, v237
	s_nop 1
	v_add_f32_dpp v235, v235, v235 quad_perm:[1,0,3,2] row_mask:0xf bank_mask:0xf
	s_nop 1
	v_add_f32_dpp v235, v235, v235 quad_perm:[2,3,0,1] row_mask:0xf bank_mask:0xf
	s_nop 1
	v_add_f32_dpp v235, v235, v235 row_half_mirror row_mask:0xf bank_mask:0xf
	s_nop 1
	v_add_f32_dpp v235, v235, v235 row_mirror row_mask:0xf bank_mask:0xf
	s_nop 0
	v_readlane_b32 s26, v235, 0
	v_readlane_b32 s27, v235, 16
	v_readlane_b32 s28, v235, 32
	v_readlane_b32 s29, v235, 48
	v_mov_b32_e32 v235, s26
	v_add_f32_e32 v235, s27, v235
	v_add_f32_e32 v235, s28, v235
	v_add_f32_e32 v235, s29, v235
	v_fmamk_f32 v235, v235, 0x3a000000, v246
	v_rsq_f32_e32 v217, v235
	s_lshl_b32 s23, s20, 13
	s_lshr_b32 s23, s23, 1
	s_add_u32 s30, s2, s23
	s_addc_u32 s31, s3, 0
	s_lshl_b32 s23, s20, 3
	s_add_u32 s6, s0, s23
	s_addc_u32 s7, s1, 0
	v_mov_b32_e32 v243, 0
	s_mov_b64 exec, 1
	global_store_dwordx2 v243, v[216:217], s[6:7]
	s_mov_b64 exec, -1
	v_pk_mul_f32 v[176:177], v[176:177], v[216:217] op_sel:[0,1] op_sel_hi:[1,1]
	v_pk_mul_f32 v[178:179], v[178:179], v[216:217] op_sel:[0,1] op_sel_hi:[1,1]
	v_pk_fma_f32 v[176:177], v[0:1], v[176:177], v[32:33]
	v_pk_fma_f32 v[178:179], v[2:3], v[178:179], v[34:35]
	v_pk_mul_f32 v[180:181], v[180:181], v[216:217] op_sel:[0,1] op_sel_hi:[1,1]
	v_pk_mul_f32 v[182:183], v[182:183], v[216:217] op_sel:[0,1] op_sel_hi:[1,1]
	v_pk_fma_f32 v[180:181], v[4:5], v[180:181], v[36:37]
	v_pk_fma_f32 v[182:183], v[6:7], v[182:183], v[38:39]
	v_cvt_pk_bf16_f32 v208, v176, v177
	v_cvt_pk_bf16_f32 v209, v178, v179
	v_cvt_pk_bf16_f32 v210, v180, v181
; __device__ __forceinline__ void ln_phase(const float* in, float* outf, bf16_t* outb, const float* g, const float* b, int wv0) {
;     ...
;   for (int row = wv; row < NTOK; row += nwv) {
;     f32x4 v[8]; float s = 0.f;
; #pragma unroll
;     for (int i = 0; i < 8; ++i) v[i] = vn[i];
;     if (row + nwv < NTOK) { const f32x4* ir = (const f32x4*)(in + (size_t)(row + nwv) * DM);
; #pragma unroll
;       for (int i = 0; i < 8; ++i) vn[i] = ir[i * 64 + lane]; }
; #pragma unroll
;     for (int i = 0; i < 8; ++i) s += v[i][0] + v[i][1] + v[i][2] + v[i][3];
;     s = wave_sum(s); const float mu = s * (1.0f / 2048.0f);
;     float sq = 0.f;
; #pragma unroll
;     for (int i = 0; i < 8; ++i) { v[i] -= mu; sq += v[i][0] * v[i][0] + v[i][1] * v[i][1] + v[i][2] * v[i][2] + v[i][3] * v[i][3]; }
;     sq = wave_sum(sq); const float rstd = __builtin_amdgcn_rsqf(sq * (1.0f / 2048.0f) + EPS);
; #pragma unroll
;     for (int i = 0; i < 8; ++i) {
;       const f32x4 y = v[i] * rstd * gg[i] + bb[i];
	v_cvt_pk_bf16_f32 v211, v182, v183
	global_store_dwordx4 v242, v[208:211], s[30:31]
	v_pk_mul_f32 v[184:185], v[184:185], v[216:217] op_sel:[0,1] op_sel_hi:[1,1]
	v_pk_mul_f32 v[186:187], v[186:187], v[216:217] op_sel:[0,1] op_sel_hi:[1,1]
	v_pk_fma_f32 v[184:185], v[8:9], v[184:185], v[40:41]
	v_pk_fma_f32 v[186:187], v[10:11], v[186:187], v[42:43]
	v_pk_mul_f32 v[188:189], v[188:189], v[216:217] op_sel:[0,1] op_sel_hi:[1,1]
	v_pk_mul_f32 v[190:191], v[190:191], v[216:217] op_sel:[0,1] op_sel_hi:[1,1]
	v_pk_fma_f32 v[188:189], v[12:13], v[188:189], v[44:45]
	v_pk_fma_f32 v[190:191], v[14:15], v[190:191], v[46:47]
	v_cvt_pk_bf16_f32 v212, v184, v185
	v_cvt_pk_bf16_f32 v213, v186, v187
	v_cvt_pk_bf16_f32 v214, v188, v189
	v_cvt_pk_bf16_f32 v215, v190, v191
	global_store_dwordx4 v242, v[212:215], s[30:31] offset:1024
	v_pk_mul_f32 v[192:193], v[192:193], v[216:217] op_sel:[0,1] op_sel_hi:[1,1]
	v_pk_mul_f32 v[194:195], v[194:195], v[216:217] op_sel:[0,1] op_sel_hi:[1,1]
	v_pk_fma_f32 v[192:193], v[16:17], v[192:193], v[48:49]
	v_pk_fma_f32 v[194:195], v[18:19], v[194:195], v[50:51]
	v_pk_mul_f32 v[196:197], v[196:197], v[216:217] op_sel:[0,1] op_sel_hi:[1,1]
	v_pk_mul_f32 v[198:199], v[198:199], v[216:217] op_sel:[0,1] op_sel_hi:[1,1]
	v_pk_fma_f32 v[196:197], v[20:21], v[196:197], v[52:53]
	v_pk_fma_f32 v[198:199], v[22:23], v[198:199], v[54:55]
	v_cvt_pk_bf16_f32 v208, v192, v193
	v_cvt_pk_bf16_f32 v209, v194, v195
	v_cvt_pk_bf16_f32 v210, v196, v197
	v_cvt_pk_bf16_f32 v211, v198, v199
	global_store_dwordx4 v242, v[208:211], s[30:31] offset:2048
	v_pk_mul_f32 v[200:201], v[200:201], v[216:217] op_sel:[0,1] op_sel_hi:[1,1]
	v_pk_mul_f32 v[202:203], v[202:203], v[216:217] op_sel:[0,1] op_sel_hi:[1,1]
	v_pk_fma_f32 v[200:201], v[24:25], v[200:201], v[56:57]
	v_pk_fma_f32 v[202:203], v[26:27], v[202:203], v[58:59]
	v_pk_mul_f32 v[204:205], v[204:205], v[216:217] op_sel:[0,1] op_sel_hi:[1,1]
	v_pk_mul_f32 v[206:207], v[206:207], v[216:217] op_sel:[0,1] op_sel_hi:[1,1]
	v_pk_fma_f32 v[204:205], v[28:29], v[204:205], v[60:61]
	v_pk_fma_f32 v[206:207], v[30:31], v[206:207], v[62:63]
	v_cvt_pk_bf16_f32 v212, v200, v201
	v_cvt_pk_bf16_f32 v213, v202, v203
	v_cvt_pk_bf16_f32 v214, v204, v205
	v_cvt_pk_bf16_f32 v215, v206, v207
	global_store_dwordx4 v242, v[212:215], s[30:31] offset:3072
	s_add_u32 s20, s20, s21
	s_cmp_ge_u32 s20, 0x4000
	s_cbranch_scc1 .Lln2a_done
	s_mul_i32 s23, s21, 3
	s_add_u32 s23, s20, s23
	s_min_u32 s23, s23, 0x3fff
	s_lshl_b32 s23, s23, 13
	s_add_u32 s24, s12, s23
	s_addc_u32 s25, s13, 0
	global_load_dwordx4 v[176:179], v240, s[24:25]
	global_load_dwordx4 v[180:183], v240, s[24:25] offset:16
	global_load_dwordx4 v[184:187], v240, s[24:25] offset:2048
	global_load_dwordx4 v[188:191], v240, s[24:25] offset:2064
	global_load_dwordx4 v[192:195], v241, s[24:25]
	global_load_dwordx4 v[196:199], v241, s[24:25] offset:16
	global_load_dwordx4 v[200:203], v241, s[24:25] offset:2048
	global_load_dwordx4 v[204:207], v241, s[24:25] offset:2064
	s_waitcnt vmcnt(39)
	v_pk_add_f32 v[236:237], v[64:65], v[66:67]
	v_pk_add_f32 v[236:237], v[236:237], v[68:69]
	v_pk_add_f32 v[236:237], v[236:237], v[70:71]
	v_pk_add_f32 v[236:237], v[236:237], v[72:73]
	v_pk_add_f32 v[236:237], v[236:237], v[74:75]
	v_pk_add_f32 v[236:237], v[236:237], v[76:77]
	v_pk_add_f32 v[236:237], v[236:237], v[78:79]
	v_pk_add_f32 v[236:237], v[236:237], v[80:81]
	v_pk_add_f32 v[236:237], v[236:237], v[82:83]
	v_pk_add_f32 v[236:237], v[236:237], v[84:85]
	v_pk_add_f32 v[236:237], v[236:237], v[86:87]
	v_pk_add_f32 v[236:237], v[236:237], v[88:89]
	v_pk_add_f32 v[236:237], v[236:237], v[90:91]
	v_pk_add_f32 v[236:237], v[236:237], v[92:93]
	v_pk_add_f32 v[236:237], v[236:237], v[94:95]
	v_add_f32_e32 v234, v236, v237
	s_nop 1
	v_add_f32_dpp v234, v234, v234 quad_perm:[1,0,3,2] row_mask:0xf bank_mask:0xf
	s_nop 1
	v_add_f32_dpp v234, v234, v234 quad_perm:[2,3,0,1] row_mask:0xf bank_mask:0xf
	s_nop 1
	v_add_f32_dpp v234, v234, v234 row_half_mirror row_mask:0xf bank_mask:0xf
	s_nop 1
	v_add_f32_dpp v234, v234, v234 row_mirror row_mask:0xf bank_mask:0xf
	s_nop 0
	v_readlane_b32 s26, v234, 0
	v_readlane_b32 s27, v234, 16
	v_readlane_b32 s28, v234, 32
	v_readlane_b32 s29, v234, 48
	v_mov_b32_e32 v234, s26
	v_add_f32_e32 v234, s27, v234
	v_add_f32_e32 v234, s28, v234
	v_add_f32_e32 v234, s29, v234
	v_mul_f32_e32 v216, 0xba000000, v234
	v_pk_add_f32 v[64:65], v[64:65], v[216:217] op_sel_hi:[1,0]
	v_pk_add_f32 v[66:67], v[66:67], v[216:217] op_sel_hi:[1,0]
	v_pk_add_f32 v[68:69], v[68:69], v[216:217] op_sel_hi:[1,0]
	v_pk_add_f32 v[70:71], v[70:71], v[216:217] op_sel_hi:[1,0]
	v_pk_add_f32 v[72:73], v[72:73], v[216:217] op_sel_hi:[1,0]
	v_pk_add_f32 v[74:75], v[74:75], v[216:217] op_sel_hi:[1,0]
	v_pk_add_f32 v[76:77], v[76:77], v[216:217] op_sel_hi:[1,0]
	v_pk_add_f32 v[78:79], v[78:79], v[216:217] op_sel_hi:[1,0]
	v_pk_add_f32 v[80:81], v[80:81], v[216:217] op_sel_hi:[1,0]
	v_pk_add_f32 v[82:83], v[82:83], v[216:217] op_sel_hi:[1,0]
	v_pk_add_f32 v[84:85], v[84:85], v[216:217] op_sel_hi:[1,0]
	v_pk_add_f32 v[86:87], v[86:87], v[216:217] op_sel_hi:[1,0]
	v_pk_add_f32 v[88:89], v[88:89], v[216:217] op_sel_hi:[1,0]
	v_pk_add_f32 v[90:91], v[90:91], v[216:217] op_sel_hi:[1,0]
	v_pk_add_f32 v[92:93], v[92:93], v[216:217] op_sel_hi:[1,0]
	v_pk_add_f32 v[94:95], v[94:95], v[216:217] op_sel_hi:[1,0]
	v_pk_mul_f32 v[236:237], v[64:65], v[64:65]
	v_pk_fma_f32 v[236:237], v[66:67], v[66:67], v[236:237]
	v_pk_fma_f32 v[236:237], v[68:69], v[68:69], v[236:237]
	v_pk_fma_f32 v[236:237], v[70:71], v[70:71], v[236:237]
	v_pk_fma_f32 v[236:237], v[72:73], v[72:73], v[236:237]
; __device__ __forceinline__ void ln_phase(const float* in, float* outf, bf16_t* outb, const float* g, const float* b, int wv0) {
;     ...
;     for (int i = 0; i < 8; ++i) { v[i] -= mu; sq += v[i][0] * v[i][0] + v[i][1] * v[i][1] + v[i][2] * v[i][2] + v[i][3] * v[i][3]; }
;     sq = wave_sum(sq); const float rstd = __builtin_amdgcn_rsqf(sq * (1.0f / 2048.0f) + EPS);
; #pragma unroll
;     for (int i = 0; i < 8; ++i) {
;       const f32x4 y = v[i] * rstd * gg[i] + bb[i];
;       ((f32x4*)(outf + (size_t)row * DM))[i * 64 + lane] = y;
;       if (outb) { u32x2 w; w.x = pk2(y[0], y[1]); w.y = pk2(y[2], y[3]); ((u32x2*)(outb + (size_t)row * DM))[i * 64 + lane] = w; } }
	v_pk_fma_f32 v[236:237], v[74:75], v[74:75], v[236:237]
	v_pk_fma_f32 v[236:237], v[76:77], v[76:77], v[236:237]
	v_pk_fma_f32 v[236:237], v[78:79], v[78:79], v[236:237]
	v_pk_fma_f32 v[236:237], v[80:81], v[80:81], v[236:237]
	v_pk_fma_f32 v[236:237], v[82:83], v[82:83], v[236:237]
	v_pk_fma_f32 v[236:237], v[84:85], v[84:85], v[236:237]
	v_pk_fma_f32 v[236:237], v[86:87], v[86:87], v[236:237]
	v_pk_fma_f32 v[236:237], v[88:89], v[88:89], v[236:237]
	v_pk_fma_f32 v[236:237], v[90:91], v[90:91], v[236:237]
	v_pk_fma_f32 v[236:237], v[92:93], v[92:93], v[236:237]
	v_pk_fma_f32 v[236:237], v[94:95], v[94:95], v[236:237]
	v_add_f32_e32 v235, v236, v237
	s_nop 1
	v_add_f32_dpp v235, v235, v235 quad_perm:[1,0,3,2] row_mask:0xf bank_mask:0xf
	s_nop 1
	v_add_f32_dpp v235, v235, v235 quad_perm:[2,3,0,1] row_mask:0xf bank_mask:0xf
	s_nop 1
	v_add_f32_dpp v235, v235, v235 row_half_mirror row_mask:0xf bank_mask:0xf
	s_nop 1
	v_add_f32_dpp v235, v235, v235 row_mirror row_mask:0xf bank_mask:0xf
	s_nop 0
	v_readlane_b32 s26, v235, 0
	v_readlane_b32 s27, v235, 16
	v_readlane_b32 s28, v235, 32
	v_readlane_b32 s29, v235, 48
	v_mov_b32_e32 v235, s26
	v_add_f32_e32 v235, s27, v235
	v_add_f32_e32 v235, s28, v235
	v_add_f32_e32 v235, s29, v235
	v_fmamk_f32 v235, v235, 0x3a000000, v246
	v_rsq_f32_e32 v217, v235
	s_lshl_b32 s23, s20, 13
	s_lshr_b32 s23, s23, 1
	s_add_u32 s30, s2, s23
	s_addc_u32 s31, s3, 0
	s_lshl_b32 s23, s20, 3
	s_add_u32 s6, s0, s23
	s_addc_u32 s7, s1, 0
	v_mov_b32_e32 v243, 0
	s_mov_b64 exec, 1
	global_store_dwordx2 v243, v[216:217], s[6:7]
	s_mov_b64 exec, -1
	v_pk_mul_f32 v[64:65], v[64:65], v[216:217] op_sel:[0,1] op_sel_hi:[1,1]
	v_pk_mul_f32 v[66:67], v[66:67], v[216:217] op_sel:[0,1] op_sel_hi:[1,1]
	v_pk_fma_f32 v[64:65], v[0:1], v[64:65], v[32:33]
	v_pk_fma_f32 v[66:67], v[2:3], v[66:67], v[34:35]
	v_pk_mul_f32 v[68:69], v[68:69], v[216:217] op_sel:[0,1] op_sel_hi:[1,1]
	v_pk_mul_f32 v[70:71], v[70:71], v[216:217] op_sel:[0,1] op_sel_hi:[1,1]
	v_pk_fma_f32 v[68:69], v[4:5], v[68:69], v[36:37]
	v_pk_fma_f32 v[70:71], v[6:7], v[70:71], v[38:39]
	v_cvt_pk_bf16_f32 v208, v64, v65
	v_cvt_pk_bf16_f32 v209, v66, v67
	v_cvt_pk_bf16_f32 v210, v68, v69
	v_cvt_pk_bf16_f32 v211, v70, v71
	global_store_dwordx4 v242, v[208:211], s[30:31]
	v_pk_mul_f32 v[72:73], v[72:73], v[216:217] op_sel:[0,1] op_sel_hi:[1,1]
	v_pk_mul_f32 v[74:75], v[74:75], v[216:217] op_sel:[0,1] op_sel_hi:[1,1]
	v_pk_fma_f32 v[72:73], v[8:9], v[72:73], v[40:41]
	v_pk_fma_f32 v[74:75], v[10:11], v[74:75], v[42:43]
	v_pk_mul_f32 v[76:77], v[76:77], v[216:217] op_sel:[0,1] op_sel_hi:[1,1]
	v_pk_mul_f32 v[78:79], v[78:79], v[216:217] op_sel:[0,1] op_sel_hi:[1,1]
	v_pk_fma_f32 v[76:77], v[12:13], v[76:77], v[44:45]
	v_pk_fma_f32 v[78:79], v[14:15], v[78:79], v[46:47]
	v_cvt_pk_bf16_f32 v212, v72, v73
	v_cvt_pk_bf16_f32 v213, v74, v75
	v_cvt_pk_bf16_f32 v214, v76, v77
	v_cvt_pk_bf16_f32 v215, v78, v79
	global_store_dwordx4 v242, v[212:215], s[30:31] offset:1024
	v_pk_mul_f32 v[80:81], v[80:81], v[216:217] op_sel:[0,1] op_sel_hi:[1,1]
	v_pk_mul_f32 v[82:83], v[82:83], v[216:217] op_sel:[0,1] op_sel_hi:[1,1]
	v_pk_fma_f32 v[80:81], v[16:17], v[80:81], v[48:49]
	v_pk_fma_f32 v[82:83], v[18:19], v[82:83], v[50:51]
	v_pk_mul_f32 v[84:85], v[84:85], v[216:217] op_sel:[0,1] op_sel_hi:[1,1]
	v_pk_mul_f32 v[86:87], v[86:87], v[216:217] op_sel:[0,1] op_sel_hi:[1,1]
	v_pk_fma_f32 v[84:85], v[20:21], v[84:85], v[52:53]
	v_pk_fma_f32 v[86:87], v[22:23], v[86:87], v[54:55]
	v_cvt_pk_bf16_f32 v208, v80, v81
	v_cvt_pk_bf16_f32 v209, v82, v83
	v_cvt_pk_bf16_f32 v210, v84, v85
	v_cvt_pk_bf16_f32 v211, v86, v87
	global_store_dwordx4 v242, v[208:211], s[30:31] offset:2048
	v_pk_mul_f32 v[88:89], v[88:89], v[216:217] op_sel:[0,1] op_sel_hi:[1,1]
	v_pk_mul_f32 v[90:91], v[90:91], v[216:217] op_sel:[0,1] op_sel_hi:[1,1]
	v_pk_fma_f32 v[88:89], v[24:25], v[88:89], v[56:57]
	v_pk_fma_f32 v[90:91], v[26:27], v[90:91], v[58:59]
	v_pk_mul_f32 v[92:93], v[92:93], v[216:217] op_sel:[0,1] op_sel_hi:[1,1]
	v_pk_mul_f32 v[94:95], v[94:95], v[216:217] op_sel:[0,1] op_sel_hi:[1,1]
	v_pk_fma_f32 v[92:93], v[28:29], v[92:93], v[60:61]
	v_pk_fma_f32 v[94:95], v[30:31], v[94:95], v[62:63]
	v_cvt_pk_bf16_f32 v212, v88, v89
	v_cvt_pk_bf16_f32 v213, v90, v91
	v_cvt_pk_bf16_f32 v214, v92, v93
	v_cvt_pk_bf16_f32 v215, v94, v95
	global_store_dwordx4 v242, v[212:215], s[30:31] offset:3072
	s_add_u32 s20, s20, s21
	s_cmp_ge_u32 s20, 0x4000
	s_cbranch_scc1 .Lln2a_done
; __device__ __forceinline__ void ln_phase(const float* in, float* outf, bf16_t* outb, const float* g, const float* b, int wv0) {
;     ...
;   for (int row = wv; row < NTOK; row += nwv) {
;     f32x4 v[8]; float s = 0.f;
; #pragma unroll
;     for (int i = 0; i < 8; ++i) v[i] = vn[i];
;     if (row + nwv < NTOK) { const f32x4* ir = (const f32x4*)(in + (size_t)(row + nwv) * DM);
; #pragma unroll
;       for (int i = 0; i < 8; ++i) vn[i] = ir[i * 64 + lane]; }
; #pragma unroll
;     for (int i = 0; i < 8; ++i) s += v[i][0] + v[i][1] + v[i][2] + v[i][3];
;     s = wave_sum(s); const float mu = s * (1.0f / 2048.0f);
;     float sq = 0.f;
; #pragma unroll
;     for (int i = 0; i < 8; ++i) { v[i] -= mu; sq += v[i][0] * v[i][0] + v[i][1] * v[i][1] + v[i][2] * v[i][2] + v[i][3] * v[i][3]; }
;     sq = wave_sum(sq); const float rstd = __builtin_amdgcn_rsqf(sq * (1.0f / 2048.0f) + EPS);
; #pragma unroll
;     for (int i = 0; i < 8; ++i) {
;       const f32x4 y = v[i] * rstd * gg[i] + bb[i];
	s_mul_i32 s23, s21, 3
	s_add_u32 s23, s20, s23
	s_min_u32 s23, s23, 0x3fff
	s_lshl_b32 s23, s23, 13
	s_add_u32 s24, s12, s23
	s_addc_u32 s25, s13, 0
	global_load_dwordx4 v[64:67], v240, s[24:25]
	global_load_dwordx4 v[68:71], v240, s[24:25] offset:16
	global_load_dwordx4 v[72:75], v240, s[24:25] offset:2048
	global_load_dwordx4 v[76:79], v240, s[24:25] offset:2064
	global_load_dwordx4 v[80:83], v241, s[24:25]
	global_load_dwordx4 v[84:87], v241, s[24:25] offset:16
	global_load_dwordx4 v[88:91], v241, s[24:25] offset:2048
	global_load_dwordx4 v[92:95], v241, s[24:25] offset:2064
	s_waitcnt vmcnt(39)
	v_pk_add_f32 v[236:237], v[96:97], v[98:99]
	v_pk_add_f32 v[236:237], v[236:237], v[100:101]
	v_pk_add_f32 v[236:237], v[236:237], v[102:103]
	v_pk_add_f32 v[236:237], v[236:237], v[104:105]
	v_pk_add_f32 v[236:237], v[236:237], v[106:107]
	v_pk_add_f32 v[236:237], v[236:237], v[108:109]
	v_pk_add_f32 v[236:237], v[236:237], v[110:111]
	v_pk_add_f32 v[236:237], v[236:237], v[112:113]
	v_pk_add_f32 v[236:237], v[236:237], v[114:115]
	v_pk_add_f32 v[236:237], v[236:237], v[116:117]
	v_pk_add_f32 v[236:237], v[236:237], v[118:119]
	v_pk_add_f32 v[236:237], v[236:237], v[120:121]
	v_pk_add_f32 v[236:237], v[236:237], v[122:123]
	v_pk_add_f32 v[236:237], v[236:237], v[124:125]
	v_pk_add_f32 v[236:237], v[236:237], v[126:127]
	v_add_f32_e32 v234, v236, v237
	s_nop 1
	v_add_f32_dpp v234, v234, v234 quad_perm:[1,0,3,2] row_mask:0xf bank_mask:0xf
	s_nop 1
	v_add_f32_dpp v234, v234, v234 quad_perm:[2,3,0,1] row_mask:0xf bank_mask:0xf
	s_nop 1
	v_add_f32_dpp v234, v234, v234 row_half_mirror row_mask:0xf bank_mask:0xf
	s_nop 1
	v_add_f32_dpp v234, v234, v234 row_mirror row_mask:0xf bank_mask:0xf
	s_nop 0
	v_readlane_b32 s26, v234, 0
	v_readlane_b32 s27, v234, 16
	v_readlane_b32 s28, v234, 32
	v_readlane_b32 s29, v234, 48
	v_mov_b32_e32 v234, s26
	v_add_f32_e32 v234, s27, v234
	v_add_f32_e32 v234, s28, v234
	v_add_f32_e32 v234, s29, v234
	v_mul_f32_e32 v216, 0xba000000, v234
	v_pk_add_f32 v[96:97], v[96:97], v[216:217] op_sel_hi:[1,0]
	v_pk_add_f32 v[98:99], v[98:99], v[216:217] op_sel_hi:[1,0]
	v_pk_add_f32 v[100:101], v[100:101], v[216:217] op_sel_hi:[1,0]
	v_pk_add_f32 v[102:103], v[102:103], v[216:217] op_sel_hi:[1,0]
	v_pk_add_f32 v[104:105], v[104:105], v[216:217] op_sel_hi:[1,0]
	v_pk_add_f32 v[106:107], v[106:107], v[216:217] op_sel_hi:[1,0]
	v_pk_add_f32 v[108:109], v[108:109], v[216:217] op_sel_hi:[1,0]
	v_pk_add_f32 v[110:111], v[110:111], v[216:217] op_sel_hi:[1,0]
	v_pk_add_f32 v[112:113], v[112:113], v[216:217] op_sel_hi:[1,0]
	v_pk_add_f32 v[114:115], v[114:115], v[216:217] op_sel_hi:[1,0]
	v_pk_add_f32 v[116:117], v[116:117], v[216:217] op_sel_hi:[1,0]
	v_pk_add_f32 v[118:119], v[118:119], v[216:217] op_sel_hi:[1,0]
	v_pk_add_f32 v[120:121], v[120:121], v[216:217] op_sel_hi:[1,0]
	v_pk_add_f32 v[122:123], v[122:123], v[216:217] op_sel_hi:[1,0]
	v_pk_add_f32 v[124:125], v[124:125], v[216:217] op_sel_hi:[1,0]
	v_pk_add_f32 v[126:127], v[126:127], v[216:217] op_sel_hi:[1,0]
	v_pk_mul_f32 v[236:237], v[96:97], v[96:97]
	v_pk_fma_f32 v[236:237], v[98:99], v[98:99], v[236:237]
	v_pk_fma_f32 v[236:237], v[100:101], v[100:101], v[236:237]
	v_pk_fma_f32 v[236:237], v[102:103], v[102:103], v[236:237]
	v_pk_fma_f32 v[236:237], v[104:105], v[104:105], v[236:237]
	v_pk_fma_f32 v[236:237], v[106:107], v[106:107], v[236:237]
	v_pk_fma_f32 v[236:237], v[108:109], v[108:109], v[236:237]
	v_pk_fma_f32 v[236:237], v[110:111], v[110:111], v[236:237]
	v_pk_fma_f32 v[236:237], v[112:113], v[112:113], v[236:237]
	v_pk_fma_f32 v[236:237], v[114:115], v[114:115], v[236:237]
	v_pk_fma_f32 v[236:237], v[116:117], v[116:117], v[236:237]
	v_pk_fma_f32 v[236:237], v[118:119], v[118:119], v[236:237]
	v_pk_fma_f32 v[236:237], v[120:121], v[120:121], v[236:237]
	v_pk_fma_f32 v[236:237], v[122:123], v[122:123], v[236:237]
	v_pk_fma_f32 v[236:237], v[124:125], v[124:125], v[236:237]
	v_pk_fma_f32 v[236:237], v[126:127], v[126:127], v[236:237]
	v_add_f32_e32 v235, v236, v237
	s_nop 1
	v_add_f32_dpp v235, v235, v235 quad_perm:[1,0,3,2] row_mask:0xf bank_mask:0xf
	s_nop 1
	v_add_f32_dpp v235, v235, v235 quad_perm:[2,3,0,1] row_mask:0xf bank_mask:0xf
	s_nop 1
	v_add_f32_dpp v235, v235, v235 row_half_mirror row_mask:0xf bank_mask:0xf
	s_nop 1
	v_add_f32_dpp v235, v235, v235 row_mirror row_mask:0xf bank_mask:0xf
	s_nop 0
	v_readlane_b32 s26, v235, 0
	v_readlane_b32 s27, v235, 16
	v_readlane_b32 s28, v235, 32
	v_readlane_b32 s29, v235, 48
	v_mov_b32_e32 v235, s26
	v_add_f32_e32 v235, s27, v235
	v_add_f32_e32 v235, s28, v235
	v_add_f32_e32 v235, s29, v235
	v_fmamk_f32 v235, v235, 0x3a000000, v246
	v_rsq_f32_e32 v217, v235
	s_lshl_b32 s23, s20, 13
	s_lshr_b32 s23, s23, 1
	s_add_u32 s30, s2, s23
	s_addc_u32 s31, s3, 0
	s_lshl_b32 s23, s20, 3
	s_add_u32 s6, s0, s23
	s_addc_u32 s7, s1, 0
	v_mov_b32_e32 v243, 0
	s_mov_b64 exec, 1
	global_store_dwordx2 v243, v[216:217], s[6:7]
	s_mov_b64 exec, -1
	v_pk_mul_f32 v[96:97], v[96:97], v[216:217] op_sel:[0,1] op_sel_hi:[1,1]
	v_pk_mul_f32 v[98:99], v[98:99], v[216:217] op_sel:[0,1] op_sel_hi:[1,1]
	v_pk_fma_f32 v[96:97], v[0:1], v[96:97], v[32:33]
	v_pk_fma_f32 v[98:99], v[2:3], v[98:99], v[34:35]
	v_pk_mul_f32 v[100:101], v[100:101], v[216:217] op_sel:[0,1] op_sel_hi:[1,1]
	v_pk_mul_f32 v[102:103], v[102:103], v[216:217] op_sel:[0,1] op_sel_hi:[1,1]
	v_pk_fma_f32 v[100:101], v[4:5], v[100:101], v[36:37]
	v_pk_fma_f32 v[102:103], v[6:7], v[102:103], v[38:39]
	v_cvt_pk_bf16_f32 v208, v96, v97
	v_cvt_pk_bf16_f32 v209, v98, v99
	v_cvt_pk_bf16_f32 v210, v100, v101
	v_cvt_pk_bf16_f32 v211, v102, v103
	global_store_dwordx4 v242, v[208:211], s[30:31]
; __device__ __forceinline__ void ln_phase(const float* in, float* outf, bf16_t* outb, const float* g, const float* b, int wv0) {
;     ...
;   for (int row = wv; row < NTOK; row += nwv) {
;     f32x4 v[8]; float s = 0.f;
; #pragma unroll
;     for (int i = 0; i < 8; ++i) v[i] = vn[i];
;     if (row + nwv < NTOK) { const f32x4* ir = (const f32x4*)(in + (size_t)(row + nwv) * DM);
; #pragma unroll
;       for (int i = 0; i < 8; ++i) vn[i] = ir[i * 64 + lane]; }
; #pragma unroll
;     for (int i = 0; i < 8; ++i) s += v[i][0] + v[i][1] + v[i][2] + v[i][3];
;     s = wave_sum(s); const float mu = s * (1.0f / 2048.0f);
;     float sq = 0.f;
; #pragma unroll
;     for (int i = 0; i < 8; ++i) { v[i] -= mu; sq += v[i][0] * v[i][0] + v[i][1] * v[i][1] + v[i][2] * v[i][2] + v[i][3] * v[i][3]; }
;     sq = wave_sum(sq); const float rstd = __builtin_amdgcn_rsqf(sq * (1.0f / 2048.0f) + EPS);
; #pragma unroll
;     for (int i = 0; i < 8; ++i) {
;       const f32x4 y = v[i] * rstd * gg[i] + bb[i];
	v_pk_mul_f32 v[104:105], v[104:105], v[216:217] op_sel:[0,1] op_sel_hi:[1,1]
	v_pk_mul_f32 v[106:107], v[106:107], v[216:217] op_sel:[0,1] op_sel_hi:[1,1]
	v_pk_fma_f32 v[104:105], v[8:9], v[104:105], v[40:41]
	v_pk_fma_f32 v[106:107], v[10:11], v[106:107], v[42:43]
	v_pk_mul_f32 v[108:109], v[108:109], v[216:217] op_sel:[0,1] op_sel_hi:[1,1]
	v_pk_mul_f32 v[110:111], v[110:111], v[216:217] op_sel:[0,1] op_sel_hi:[1,1]
	v_pk_fma_f32 v[108:109], v[12:13], v[108:109], v[44:45]
	v_pk_fma_f32 v[110:111], v[14:15], v[110:111], v[46:47]
	v_cvt_pk_bf16_f32 v212, v104, v105
	v_cvt_pk_bf16_f32 v213, v106, v107
	v_cvt_pk_bf16_f32 v214, v108, v109
	v_cvt_pk_bf16_f32 v215, v110, v111
	global_store_dwordx4 v242, v[212:215], s[30:31] offset:1024
	v_pk_mul_f32 v[112:113], v[112:113], v[216:217] op_sel:[0,1] op_sel_hi:[1,1]
	v_pk_mul_f32 v[114:115], v[114:115], v[216:217] op_sel:[0,1] op_sel_hi:[1,1]
	v_pk_fma_f32 v[112:113], v[16:17], v[112:113], v[48:49]
	v_pk_fma_f32 v[114:115], v[18:19], v[114:115], v[50:51]
	v_pk_mul_f32 v[116:117], v[116:117], v[216:217] op_sel:[0,1] op_sel_hi:[1,1]
	v_pk_mul_f32 v[118:119], v[118:119], v[216:217] op_sel:[0,1] op_sel_hi:[1,1]
	v_pk_fma_f32 v[116:117], v[20:21], v[116:117], v[52:53]
	v_pk_fma_f32 v[118:119], v[22:23], v[118:119], v[54:55]
	v_cvt_pk_bf16_f32 v208, v112, v113
	v_cvt_pk_bf16_f32 v209, v114, v115
	v_cvt_pk_bf16_f32 v210, v116, v117
	v_cvt_pk_bf16_f32 v211, v118, v119
	global_store_dwordx4 v242, v[208:211], s[30:31] offset:2048
	v_pk_mul_f32 v[120:121], v[120:121], v[216:217] op_sel:[0,1] op_sel_hi:[1,1]
	v_pk_mul_f32 v[122:123], v[122:123], v[216:217] op_sel:[0,1] op_sel_hi:[1,1]
	v_pk_fma_f32 v[120:121], v[24:25], v[120:121], v[56:57]
	v_pk_fma_f32 v[122:123], v[26:27], v[122:123], v[58:59]
	v_pk_mul_f32 v[124:125], v[124:125], v[216:217] op_sel:[0,1] op_sel_hi:[1,1]
	v_pk_mul_f32 v[126:127], v[126:127], v[216:217] op_sel:[0,1] op_sel_hi:[1,1]
	v_pk_fma_f32 v[124:125], v[28:29], v[124:125], v[60:61]
	v_pk_fma_f32 v[126:127], v[30:31], v[126:127], v[62:63]
	v_cvt_pk_bf16_f32 v212, v120, v121
	v_cvt_pk_bf16_f32 v213, v122, v123
	v_cvt_pk_bf16_f32 v214, v124, v125
	v_cvt_pk_bf16_f32 v215, v126, v127
	global_store_dwordx4 v242, v[212:215], s[30:31] offset:3072
	s_add_u32 s20, s20, s21
	s_cmp_ge_u32 s20, 0x4000
	s_cbranch_scc1 .Lln2a_done
	s_mul_i32 s23, s21, 3
	s_add_u32 s23, s20, s23
	s_min_u32 s23, s23, 0x3fff
	s_lshl_b32 s23, s23, 13
	s_add_u32 s24, s12, s23
	s_addc_u32 s25, s13, 0
	global_load_dwordx4 v[96:99], v240, s[24:25]
	global_load_dwordx4 v[100:103], v240, s[24:25] offset:16
	global_load_dwordx4 v[104:107], v240, s[24:25] offset:2048
	global_load_dwordx4 v[108:111], v240, s[24:25] offset:2064
	global_load_dwordx4 v[112:115], v241, s[24:25]
	global_load_dwordx4 v[116:119], v241, s[24:25] offset:16
	global_load_dwordx4 v[120:123], v241, s[24:25] offset:2048
	global_load_dwordx4 v[124:127], v241, s[24:25] offset:2064
	s_waitcnt vmcnt(39)
	v_pk_add_f32 v[236:237], v[128:129], v[130:131]
	v_pk_add_f32 v[236:237], v[236:237], v[132:133]
	v_pk_add_f32 v[236:237], v[236:237], v[134:135]
	v_pk_add_f32 v[236:237], v[236:237], v[136:137]
	v_pk_add_f32 v[236:237], v[236:237], v[138:139]
	v_pk_add_f32 v[236:237], v[236:237], v[140:141]
	v_pk_add_f32 v[236:237], v[236:237], v[142:143]
	v_pk_add_f32 v[236:237], v[236:237], v[144:145]
	v_pk_add_f32 v[236:237], v[236:237], v[146:147]
	v_pk_add_f32 v[236:237], v[236:237], v[148:149]
	v_pk_add_f32 v[236:237], v[236:237], v[150:151]
	v_pk_add_f32 v[236:237], v[236:237], v[152:153]
	v_pk_add_f32 v[236:237], v[236:237], v[154:155]
	v_pk_add_f32 v[236:237], v[236:237], v[156:157]
	v_pk_add_f32 v[236:237], v[236:237], v[158:159]
	v_add_f32_e32 v234, v236, v237
	s_nop 1
	v_add_f32_dpp v234, v234, v234 quad_perm:[1,0,3,2] row_mask:0xf bank_mask:0xf
	s_nop 1
	v_add_f32_dpp v234, v234, v234 quad_perm:[2,3,0,1] row_mask:0xf bank_mask:0xf
	s_nop 1
	v_add_f32_dpp v234, v234, v234 row_half_mirror row_mask:0xf bank_mask:0xf
	s_nop 1
	v_add_f32_dpp v234, v234, v234 row_mirror row_mask:0xf bank_mask:0xf
	s_nop 0
	v_readlane_b32 s26, v234, 0
	v_readlane_b32 s27, v234, 16
	v_readlane_b32 s28, v234, 32
	v_readlane_b32 s29, v234, 48
	v_mov_b32_e32 v234, s26
	v_add_f32_e32 v234, s27, v234
	v_add_f32_e32 v234, s28, v234
	v_add_f32_e32 v234, s29, v234
	v_mul_f32_e32 v216, 0xba000000, v234
	v_pk_add_f32 v[128:129], v[128:129], v[216:217] op_sel_hi:[1,0]
	v_pk_add_f32 v[130:131], v[130:131], v[216:217] op_sel_hi:[1,0]
	v_pk_add_f32 v[132:133], v[132:133], v[216:217] op_sel_hi:[1,0]
	v_pk_add_f32 v[134:135], v[134:135], v[216:217] op_sel_hi:[1,0]
	v_pk_add_f32 v[136:137], v[136:137], v[216:217] op_sel_hi:[1,0]
	v_pk_add_f32 v[138:139], v[138:139], v[216:217] op_sel_hi:[1,0]
	v_pk_add_f32 v[140:141], v[140:141], v[216:217] op_sel_hi:[1,0]
	v_pk_add_f32 v[142:143], v[142:143], v[216:217] op_sel_hi:[1,0]
	v_pk_add_f32 v[144:145], v[144:145], v[216:217] op_sel_hi:[1,0]
	v_pk_add_f32 v[146:147], v[146:147], v[216:217] op_sel_hi:[1,0]
	v_pk_add_f32 v[148:149], v[148:149], v[216:217] op_sel_hi:[1,0]
	v_pk_add_f32 v[150:151], v[150:151], v[216:217] op_sel_hi:[1,0]
	v_pk_add_f32 v[152:153], v[152:153], v[216:217] op_sel_hi:[1,0]
; __device__ __forceinline__ void ln_phase(const float* in, float* outf, bf16_t* outb, const float* g, const float* b, int wv0) {
;     ...
;     for (int i = 0; i < 8; ++i) { v[i] -= mu; sq += v[i][0] * v[i][0] + v[i][1] * v[i][1] + v[i][2] * v[i][2] + v[i][3] * v[i][3]; }
;     sq = wave_sum(sq); const float rstd = __builtin_amdgcn_rsqf(sq * (1.0f / 2048.0f) + EPS);
; #pragma unroll
;     for (int i = 0; i < 8; ++i) {
;       const f32x4 y = v[i] * rstd * gg[i] + bb[i];
;       ((f32x4*)(outf + (size_t)row * DM))[i * 64 + lane] = y;
;       if (outb) { u32x2 w; w.x = pk2(y[0], y[1]); w.y = pk2(y[2], y[3]); ((u32x2*)(outb + (size_t)row * DM))[i * 64 + lane] = w; } }
	v_pk_add_f32 v[154:155], v[154:155], v[216:217] op_sel_hi:[1,0]
	v_pk_add_f32 v[156:157], v[156:157], v[216:217] op_sel_hi:[1,0]
	v_pk_add_f32 v[158:159], v[158:159], v[216:217] op_sel_hi:[1,0]
	v_pk_mul_f32 v[236:237], v[128:129], v[128:129]
	v_pk_fma_f32 v[236:237], v[130:131], v[130:131], v[236:237]
	v_pk_fma_f32 v[236:237], v[132:133], v[132:133], v[236:237]
	v_pk_fma_f32 v[236:237], v[134:135], v[134:135], v[236:237]
	v_pk_fma_f32 v[236:237], v[136:137], v[136:137], v[236:237]
	v_pk_fma_f32 v[236:237], v[138:139], v[138:139], v[236:237]
	v_pk_fma_f32 v[236:237], v[140:141], v[140:141], v[236:237]
	v_pk_fma_f32 v[236:237], v[142:143], v[142:143], v[236:237]
	v_pk_fma_f32 v[236:237], v[144:145], v[144:145], v[236:237]
	v_pk_fma_f32 v[236:237], v[146:147], v[146:147], v[236:237]
	v_pk_fma_f32 v[236:237], v[148:149], v[148:149], v[236:237]
	v_pk_fma_f32 v[236:237], v[150:151], v[150:151], v[236:237]
	v_pk_fma_f32 v[236:237], v[152:153], v[152:153], v[236:237]
	v_pk_fma_f32 v[236:237], v[154:155], v[154:155], v[236:237]
	v_pk_fma_f32 v[236:237], v[156:157], v[156:157], v[236:237]
	v_pk_fma_f32 v[236:237], v[158:159], v[158:159], v[236:237]
	v_add_f32_e32 v235, v236, v237
	s_nop 1
	v_add_f32_dpp v235, v235, v235 quad_perm:[1,0,3,2] row_mask:0xf bank_mask:0xf
	s_nop 1
	v_add_f32_dpp v235, v235, v235 quad_perm:[2,3,0,1] row_mask:0xf bank_mask:0xf
	s_nop 1
	v_add_f32_dpp v235, v235, v235 row_half_mirror row_mask:0xf bank_mask:0xf
	s_nop 1
	v_add_f32_dpp v235, v235, v235 row_mirror row_mask:0xf bank_mask:0xf
	s_nop 0
	v_readlane_b32 s26, v235, 0
	v_readlane_b32 s27, v235, 16
	v_readlane_b32 s28, v235, 32
	v_readlane_b32 s29, v235, 48
	v_mov_b32_e32 v235, s26
	v_add_f32_e32 v235, s27, v235
	v_add_f32_e32 v235, s28, v235
	v_add_f32_e32 v235, s29, v235
	v_fmamk_f32 v235, v235, 0x3a000000, v246
	v_rsq_f32_e32 v217, v235
	s_lshl_b32 s23, s20, 13
	s_lshr_b32 s23, s23, 1
	s_add_u32 s30, s2, s23
	s_addc_u32 s31, s3, 0
	s_lshl_b32 s23, s20, 3
	s_add_u32 s6, s0, s23
	s_addc_u32 s7, s1, 0
	v_mov_b32_e32 v243, 0
	s_mov_b64 exec, 1
	global_store_dwordx2 v243, v[216:217], s[6:7]
	s_mov_b64 exec, -1
	v_pk_mul_f32 v[128:129], v[128:129], v[216:217] op_sel:[0,1] op_sel_hi:[1,1]
	v_pk_mul_f32 v[130:131], v[130:131], v[216:217] op_sel:[0,1] op_sel_hi:[1,1]
	v_pk_fma_f32 v[128:129], v[0:1], v[128:129], v[32:33]
	v_pk_fma_f32 v[130:131], v[2:3], v[130:131], v[34:35]
	v_pk_mul_f32 v[132:133], v[132:133], v[216:217] op_sel:[0,1] op_sel_hi:[1,1]
	v_pk_mul_f32 v[134:135], v[134:135], v[216:217] op_sel:[0,1] op_sel_hi:[1,1]
	v_pk_fma_f32 v[132:133], v[4:5], v[132:133], v[36:37]
	v_pk_fma_f32 v[134:135], v[6:7], v[134:135], v[38:39]
	v_cvt_pk_bf16_f32 v208, v128, v129
	v_cvt_pk_bf16_f32 v209, v130, v131
	v_cvt_pk_bf16_f32 v210, v132, v133
	v_cvt_pk_bf16_f32 v211, v134, v135
	global_store_dwordx4 v242, v[208:211], s[30:31]
	v_pk_mul_f32 v[136:137], v[136:137], v[216:217] op_sel:[0,1] op_sel_hi:[1,1]
	v_pk_mul_f32 v[138:139], v[138:139], v[216:217] op_sel:[0,1] op_sel_hi:[1,1]
	v_pk_fma_f32 v[136:137], v[8:9], v[136:137], v[40:41]
	v_pk_fma_f32 v[138:139], v[10:11], v[138:139], v[42:43]
	v_pk_mul_f32 v[140:141], v[140:141], v[216:217] op_sel:[0,1] op_sel_hi:[1,1]
	v_pk_mul_f32 v[142:143], v[142:143], v[216:217] op_sel:[0,1] op_sel_hi:[1,1]
	v_pk_fma_f32 v[140:141], v[12:13], v[140:141], v[44:45]
	v_pk_fma_f32 v[142:143], v[14:15], v[142:143], v[46:47]
	v_cvt_pk_bf16_f32 v212, v136, v137
	v_cvt_pk_bf16_f32 v213, v138, v139
	v_cvt_pk_bf16_f32 v214, v140, v141
	v_cvt_pk_bf16_f32 v215, v142, v143
	global_store_dwordx4 v242, v[212:215], s[30:31] offset:1024
	v_pk_mul_f32 v[144:145], v[144:145], v[216:217] op_sel:[0,1] op_sel_hi:[1,1]
	v_pk_mul_f32 v[146:147], v[146:147], v[216:217] op_sel:[0,1] op_sel_hi:[1,1]
	v_pk_fma_f32 v[144:145], v[16:17], v[144:145], v[48:49]
	v_pk_fma_f32 v[146:147], v[18:19], v[146:147], v[50:51]
	v_pk_mul_f32 v[148:149], v[148:149], v[216:217] op_sel:[0,1] op_sel_hi:[1,1]
	v_pk_mul_f32 v[150:151], v[150:151], v[216:217] op_sel:[0,1] op_sel_hi:[1,1]
	v_pk_fma_f32 v[148:149], v[20:21], v[148:149], v[52:53]
	v_pk_fma_f32 v[150:151], v[22:23], v[150:151], v[54:55]
	v_cvt_pk_bf16_f32 v208, v144, v145
	v_cvt_pk_bf16_f32 v209, v146, v147
	v_cvt_pk_bf16_f32 v210, v148, v149
	v_cvt_pk_bf16_f32 v211, v150, v151
	global_store_dwordx4 v242, v[208:211], s[30:31] offset:2048
	v_pk_mul_f32 v[152:153], v[152:153], v[216:217] op_sel:[0,1] op_sel_hi:[1,1]
	v_pk_mul_f32 v[154:155], v[154:155], v[216:217] op_sel:[0,1] op_sel_hi:[1,1]
	v_pk_fma_f32 v[152:153], v[24:25], v[152:153], v[56:57]
	v_pk_fma_f32 v[154:155], v[26:27], v[154:155], v[58:59]
	v_pk_mul_f32 v[156:157], v[156:157], v[216:217] op_sel:[0,1] op_sel_hi:[1,1]
	v_pk_mul_f32 v[158:159], v[158:159], v[216:217] op_sel:[0,1] op_sel_hi:[1,1]
	v_pk_fma_f32 v[156:157], v[28:29], v[156:157], v[60:61]
	v_pk_fma_f32 v[158:159], v[30:31], v[158:159], v[62:63]
	v_cvt_pk_bf16_f32 v212, v152, v153
	v_cvt_pk_bf16_f32 v213, v154, v155
	v_cvt_pk_bf16_f32 v214, v156, v157
	v_cvt_pk_bf16_f32 v215, v158, v159
	global_store_dwordx4 v242, v[212:215], s[30:31] offset:3072
	s_add_u32 s20, s20, s21
	s_cmp_ge_u32 s20, 0x4000
	s_cbranch_scc1 .Lln2a_done
	s_branch .Lln2a_loop
